# a12: + s_setprio 1 around the post-barrier DMA-issue/MFMA segment of every GEMM k-tile (0 elsewhere)
# speedup vs baseline: 1.0061x; 1.0061x over previous
; #define GBAR() do { asm volatile("s_waitcnt vmcnt(0) lgkmcnt(0)" ::: "memory"); __builtin_amdgcn_s_barrier(); } while (0)
; template <int EPI, bool GUARD>
; DEVI void gemm_tile(const Params& p, const bf16_t* __restrict__ A, int lda, const bf16_t* __restrict__ Bt, int ldb, int K,
;                           int row_base, int row_lo, int row_hi, int tile_n, int layer, int which, char* lds) {
;     ...
;   const int swz = c16 >> 1;
;   int koff[2];
; #pragma unroll
;   for (int ks = 0; ks < 2; ++ks) koff[ks] = ((ks * 4 + q4) ^ swz) << 4;
;   const int arow = (wr * 64 + c16) * 128, brow = 16384 + (wc * 64 + c16) * 128;
;     ...
;   GISSUE(0, 0); GBAR();
;   for (int k0 = 0; k0 < K; k0 += 128) {
;     GISSUE(k0 + 64, 1);
;     KSTEPS(0);
;     GBAR();
;     if (k0 + 128 < K) GISSUE(k0 + 128, 0);
;     KSTEPS(1);
;     GBAR();
;   }
.LBB0_536:
	ds_read_b128 v[82:85], v64 offset:32768
	ds_read_b128 v[86:89], v105 offset:49152
	ds_read_b128 v[90:93], v64 offset:34816
	ds_read_b128 v[94:97], v105 offset:51200
	ds_read_b128 v[108:111], v105 offset:53248
	ds_read_b128 v[112:115], v105 offset:55296
	s_addk_i32 s61, 0x80
	s_waitcnt lgkmcnt(0)
	v_mfma_f32_16x16x32_bf16 v[0:3], v[82:85], v[86:89], v[0:3]
	s_add_u32 s16, s16, 0x100
	s_addc_u32 s17, s17, 0
	s_andn2_b64 vcc, exec, s[18:19]
	v_mfma_f32_16x16x32_bf16 v[4:7], v[82:85], v[94:97], v[4:7]
	v_mfma_f32_16x16x32_bf16 v[8:11], v[82:85], v[108:111], v[8:11]
	v_mfma_f32_16x16x32_bf16 v[12:15], v[82:85], v[112:115], v[12:15]
	v_mfma_f32_16x16x32_bf16 v[16:19], v[90:93], v[86:89], v[16:19]
	v_mfma_f32_16x16x32_bf16 v[20:23], v[90:93], v[94:97], v[20:23]
	v_mfma_f32_16x16x32_bf16 v[24:27], v[90:93], v[108:111], v[24:27]
	v_mfma_f32_16x16x32_bf16 v[28:31], v[90:93], v[112:115], v[28:31]
	ds_read_b128 v[82:85], v64 offset:36864
	ds_read_b128 v[90:93], v64 offset:38912
	s_waitcnt lgkmcnt(0)
	v_mfma_f32_16x16x32_bf16 v[116:119], v[82:85], v[86:89], v[32:35]
	s_nop 2
	ds_read_b128 v[32:35], v106 offset:32768
	v_mfma_f32_16x16x32_bf16 v[120:123], v[82:85], v[94:97], v[36:39]
	v_mfma_f32_16x16x32_bf16 v[124:127], v[82:85], v[108:111], v[40:43]
	v_mfma_f32_16x16x32_bf16 v[82:85], v[82:85], v[112:115], v[44:47]
	v_mfma_f32_16x16x32_bf16 v[86:89], v[90:93], v[86:89], v[48:51]
	v_mfma_f32_16x16x32_bf16 v[94:97], v[90:93], v[94:97], v[52:55]
	v_mfma_f32_16x16x32_bf16 v[108:111], v[90:93], v[108:111], v[56:59]
	v_mfma_f32_16x16x32_bf16 v[90:93], v[90:93], v[112:115], v[60:63]
	ds_read_b128 v[112:115], v107 offset:49152
	ds_read_b128 v[36:39], v106 offset:34816
	ds_read_b128 v[128:131], v107 offset:51200
	ds_read_b128 v[132:135], v107 offset:53248
	ds_read_b128 v[136:139], v107 offset:55296
	s_waitcnt lgkmcnt(0)
	v_mfma_f32_16x16x32_bf16 v[56:59], v[32:35], v[112:115], v[0:3]
	v_mfma_f32_16x16x32_bf16 v[60:63], v[32:35], v[132:135], v[8:11]
	s_nop 1
	ds_read_b128 v[0:3], v106 offset:36864
	ds_read_b128 v[8:11], v106 offset:38912
	s_waitcnt vmcnt(0) lgkmcnt(0)
	s_barrier
	s_cbranch_vccz .Lge0_exit1
	s_setprio 1
	v_mfma_f32_16x16x32_bf16 v[48:51], v[32:35], v[128:131], v[4:7]
	s_add_i32 m0, s45, 0x8000
	v_lshl_add_u64 v[246:247], s[16:17], 0, v[66:67]
	v_lshl_add_u64 v[246:247], v[246:247], 0, s[4:5]
	global_load_lds_dwordx4 v[246:247], off
	v_mfma_f32_16x16x32_bf16 v[52:55], v[32:35], v[136:139], v[12:15]
	s_add_i32 m0, s45, 0xc000
	v_lshl_add_u64 v[246:247], s[16:17], 0, v[74:75]
	v_lshl_add_u64 v[246:247], v[246:247], 0, s[6:7]
	global_load_lds_dwordx4 v[246:247], off
	v_mfma_f32_16x16x32_bf16 v[40:43], v[36:39], v[112:115], v[16:19]
	s_add_i32 m0, s45, 0x8400
	v_lshl_add_u64 v[246:247], s[16:17], 0, v[68:69]
	v_lshl_add_u64 v[246:247], v[246:247], 0, s[4:5]
	global_load_lds_dwordx4 v[246:247], off
	v_mfma_f32_16x16x32_bf16 v[32:35], v[36:39], v[128:131], v[20:23]
	s_add_i32 m0, s45, 0xc400
	v_lshl_add_u64 v[246:247], s[16:17], 0, v[76:77]
	v_lshl_add_u64 v[246:247], v[246:247], 0, s[6:7]
	global_load_lds_dwordx4 v[246:247], off
	v_mfma_f32_16x16x32_bf16 v[44:47], v[36:39], v[132:135], v[24:27]
	s_add_i32 m0, s45, 0x8800
	v_lshl_add_u64 v[246:247], s[16:17], 0, v[70:71]
	v_lshl_add_u64 v[246:247], v[246:247], 0, s[4:5]
	global_load_lds_dwordx4 v[246:247], off
	v_mfma_f32_16x16x32_bf16 v[36:39], v[36:39], v[136:139], v[28:31]
	s_add_i32 m0, s45, 0xc800
	v_lshl_add_u64 v[246:247], s[16:17], 0, v[78:79]
	v_lshl_add_u64 v[246:247], v[246:247], 0, s[6:7]
	global_load_lds_dwordx4 v[246:247], off
	s_waitcnt lgkmcnt(0)
	v_mfma_f32_16x16x32_bf16 v[24:27], v[0:3], v[112:115], v[116:119]
	s_add_i32 m0, s45, 0x8c00
	v_lshl_add_u64 v[246:247], s[16:17], 0, v[72:73]
	v_lshl_add_u64 v[246:247], v[246:247], 0, s[4:5]
	global_load_lds_dwordx4 v[246:247], off
	v_mfma_f32_16x16x32_bf16 v[16:19], v[0:3], v[128:131], v[120:123]
	s_add_i32 m0, s45, 0xcc00
	v_lshl_add_u64 v[246:247], s[16:17], 0, v[80:81]
	v_lshl_add_u64 v[246:247], v[246:247], 0, s[6:7]
	global_load_lds_dwordx4 v[246:247], off
	v_mfma_f32_16x16x32_bf16 v[28:31], v[0:3], v[132:135], v[124:127]
	v_mfma_f32_16x16x32_bf16 v[20:23], v[0:3], v[136:139], v[82:85]
	v_mfma_f32_16x16x32_bf16 v[4:7], v[8:11], v[112:115], v[86:89]
	v_mfma_f32_16x16x32_bf16 v[0:3], v[8:11], v[128:131], v[94:97]
	v_mfma_f32_16x16x32_bf16 v[12:15], v[8:11], v[132:135], v[108:111]
	v_mfma_f32_16x16x32_bf16 v[8:11], v[8:11], v[136:139], v[90:93]
	s_cmpk_gt_u32 s61, 0x37f
	s_setprio 0
	s_branch .Lge0_k0

; #define GBAR() do { asm volatile("s_waitcnt vmcnt(0) lgkmcnt(0)" ::: "memory"); __builtin_amdgcn_s_barrier(); } while (0)
; template <int EPI, bool GUARD>
; DEVI void gemm_tile(const Params& p, const bf16_t* __restrict__ A, int lda, const bf16_t* __restrict__ Bt, int ldb, int K,
;                           int row_base, int row_lo, int row_hi, int tile_n, int layer, int which, char* lds) {
;     ...
;   const int swz = c16 >> 1;
;   int koff[2];
; #pragma unroll
;   for (int ks = 0; ks < 2; ++ks) koff[ks] = ((ks * 4 + q4) ^ swz) << 4;
;   const int arow = (wr * 64 + c16) * 128, brow = 16384 + (wc * 64 + c16) * 128;
;     ...
;   GISSUE(0, 0); GBAR();
;   for (int k0 = 0; k0 < K; k0 += 128) {
;     GISSUE(k0 + 64, 1);
;     KSTEPS(0);
;     GBAR();
;     if (k0 + 128 < K) GISSUE(k0 + 128, 0);
;     KSTEPS(1);
;     GBAR();
;   }
.Lge0_k0:
	ds_read_b128 v[108:111], v64
	ds_read_b128 v[112:115], v105 offset:16384
	ds_read_b128 v[116:119], v64 offset:2048
	ds_read_b128 v[120:123], v105 offset:18432
	ds_read_b128 v[124:127], v105 offset:20480
	ds_read_b128 v[128:131], v105 offset:22528
	s_waitcnt lgkmcnt(0)
	v_mfma_f32_16x16x32_bf16 v[56:59], v[108:111], v[112:115], v[56:59]
	s_cselect_b64 s[18:19], -1, 0
	s_and_b64 vcc, exec, s[18:19]
	v_mfma_f32_16x16x32_bf16 v[48:51], v[108:111], v[120:123], v[48:51]
	v_mfma_f32_16x16x32_bf16 v[60:63], v[108:111], v[124:127], v[60:63]
	v_mfma_f32_16x16x32_bf16 v[52:55], v[108:111], v[128:131], v[52:55]
	v_mfma_f32_16x16x32_bf16 v[40:43], v[116:119], v[112:115], v[40:43]
	v_mfma_f32_16x16x32_bf16 v[32:35], v[116:119], v[120:123], v[32:35]
	v_mfma_f32_16x16x32_bf16 v[44:47], v[116:119], v[124:127], v[44:47]
	v_mfma_f32_16x16x32_bf16 v[36:39], v[116:119], v[128:131], v[36:39]
	ds_read_b128 v[108:111], v64 offset:4096
	ds_read_b128 v[116:119], v64 offset:6144
	s_waitcnt lgkmcnt(0)
	v_mfma_f32_16x16x32_bf16 v[140:143], v[108:111], v[124:127], v[28:31]
	v_mfma_f32_16x16x32_bf16 v[124:127], v[116:119], v[124:127], v[12:15]
	s_nop 2
	ds_read_b128 v[12:15], v106
	v_mfma_f32_16x16x32_bf16 v[132:135], v[108:111], v[112:115], v[24:27]
	v_mfma_f32_16x16x32_bf16 v[136:139], v[108:111], v[120:123], v[16:19]
	v_mfma_f32_16x16x32_bf16 v[108:111], v[108:111], v[128:131], v[20:23]
	v_mfma_f32_16x16x32_bf16 v[112:115], v[116:119], v[112:115], v[4:7]
	v_mfma_f32_16x16x32_bf16 v[120:123], v[116:119], v[120:123], v[0:3]
	v_mfma_f32_16x16x32_bf16 v[116:119], v[116:119], v[128:131], v[8:11]
	ds_read_b128 v[128:131], v107 offset:16384
	ds_read_b128 v[28:31], v106 offset:2048
	ds_read_b128 v[144:147], v107 offset:18432
	s_waitcnt lgkmcnt(0)
	v_mfma_f32_16x16x32_bf16 v[0:3], v[12:15], v[128:131], v[56:59]
	s_nop 2
	ds_read_b128 v[56:59], v107 offset:20480
	ds_read_b128 v[148:151], v107 offset:22528
	s_waitcnt lgkmcnt(0)
	v_mfma_f32_16x16x32_bf16 v[8:11], v[12:15], v[56:59], v[60:63]
	v_mfma_f32_16x16x32_bf16 v[24:27], v[28:31], v[56:59], v[44:47]
	s_nop 2
	ds_read_b128 v[44:47], v106 offset:4096
	ds_read_b128 v[60:63], v106 offset:6144
	s_waitcnt vmcnt(0) lgkmcnt(0)
	s_barrier
	s_cbranch_vccnz .Lge0_last0
	s_setprio 1
	v_mfma_f32_16x16x32_bf16 v[4:7], v[12:15], v[144:147], v[48:51]
	s_mov_b32 m0, s45
	v_lshl_add_u64 v[246:247], s[16:17], 0, v[66:67]
	v_lshl_add_u64 v[246:247], v[246:247], 0, s[8:9]
	global_load_lds_dwordx4 v[246:247], off
	v_mfma_f32_16x16x32_bf16 v[12:15], v[12:15], v[148:151], v[52:55]
	s_mov_b32 m0, s46
	v_lshl_add_u64 v[246:247], s[16:17], 0, v[74:75]
	v_lshl_add_u64 v[246:247], v[246:247], 0, s[12:13]
	global_load_lds_dwordx4 v[246:247], off
	v_mfma_f32_16x16x32_bf16 v[16:19], v[28:31], v[128:131], v[40:43]
	s_mov_b32 m0, s47
	v_lshl_add_u64 v[246:247], s[16:17], 0, v[68:69]
	v_lshl_add_u64 v[246:247], v[246:247], 0, s[8:9]
	global_load_lds_dwordx4 v[246:247], off
	v_mfma_f32_16x16x32_bf16 v[20:23], v[28:31], v[144:147], v[32:35]
	s_mov_b32 m0, s54
	v_lshl_add_u64 v[246:247], s[16:17], 0, v[76:77]
	v_lshl_add_u64 v[246:247], v[246:247], 0, s[12:13]
	global_load_lds_dwordx4 v[246:247], off
	v_mfma_f32_16x16x32_bf16 v[28:31], v[28:31], v[148:151], v[36:39]
	s_mov_b32 m0, s55
	v_lshl_add_u64 v[246:247], s[16:17], 0, v[70:71]
	v_lshl_add_u64 v[246:247], v[246:247], 0, s[8:9]
	global_load_lds_dwordx4 v[246:247], off
	s_waitcnt lgkmcnt(0)
	v_mfma_f32_16x16x32_bf16 v[32:35], v[44:47], v[128:131], v[132:135]
	s_mov_b32 m0, s58
	v_lshl_add_u64 v[246:247], s[16:17], 0, v[78:79]
	v_lshl_add_u64 v[246:247], v[246:247], 0, s[12:13]
	global_load_lds_dwordx4 v[246:247], off
	v_mfma_f32_16x16x32_bf16 v[36:39], v[44:47], v[144:147], v[136:139]
	s_mov_b32 m0, s59
	v_lshl_add_u64 v[246:247], s[16:17], 0, v[72:73]
	v_lshl_add_u64 v[246:247], v[246:247], 0, s[8:9]
	global_load_lds_dwordx4 v[246:247], off
	v_mfma_f32_16x16x32_bf16 v[40:43], v[44:47], v[56:59], v[140:143]
	s_mov_b32 m0, s60
	v_lshl_add_u64 v[246:247], s[16:17], 0, v[80:81]
	v_lshl_add_u64 v[246:247], v[246:247], 0, s[12:13]
	global_load_lds_dwordx4 v[246:247], off
	v_mfma_f32_16x16x32_bf16 v[44:47], v[44:47], v[148:151], v[108:111]
	v_mfma_f32_16x16x32_bf16 v[48:51], v[60:63], v[128:131], v[112:115]
	v_mfma_f32_16x16x32_bf16 v[52:55], v[60:63], v[144:147], v[120:123]
	v_mfma_f32_16x16x32_bf16 v[56:59], v[60:63], v[56:59], v[124:127]
	v_mfma_f32_16x16x32_bf16 v[60:63], v[60:63], v[148:151], v[116:119]
	s_setprio 0
	s_branch .LBB0_536

; #define GBAR() do { asm volatile("s_waitcnt vmcnt(0) lgkmcnt(0)" ::: "memory"); __builtin_amdgcn_s_barrier(); } while (0)
; template <int EPI, bool GUARD>
; DEVI void gemm_tile(const Params& p, const bf16_t* __restrict__ A, int lda, const bf16_t* __restrict__ Bt, int ldb, int K,
;                           int row_base, int row_lo, int row_hi, int tile_n, int layer, int which, char* lds) {
;     ...
;   const int swz = c16 >> 1;
;   int koff[2];
; #pragma unroll
;   for (int ks = 0; ks < 2; ++ks) koff[ks] = ((ks * 4 + q4) ^ swz) << 4;
;   const int arow = (wr * 64 + c16) * 128, brow = 16384 + (wc * 64 + c16) * 128;
;     ...
;   GISSUE(0, 0); GBAR();
;   for (int k0 = 0; k0 < K; k0 += 128) {
;     GISSUE(k0 + 64, 1);
;     KSTEPS(0);
;     GBAR();
;     if (k0 + 128 < K) GISSUE(k0 + 128, 0);
;     KSTEPS(1);
;     GBAR();
;   }
.LBB0_667:
	ds_read_b128 v[82:85], v64 offset:32768
	ds_read_b128 v[86:89], v111 offset:49152
	ds_read_b128 v[90:93], v64 offset:34816
	ds_read_b128 v[94:97], v111 offset:51200
	ds_read_b128 v[114:117], v111 offset:53248
	ds_read_b128 v[118:121], v111 offset:55296
	s_addk_i32 s9, 0x80
	s_waitcnt lgkmcnt(0)
	v_mfma_f32_16x16x32_bf16 v[0:3], v[82:85], v[86:89], v[0:3]
	s_add_u32 s4, s4, 0x100
	s_addc_u32 s5, s5, 0
	s_and_b64 vcc, exec, s[6:7]
	v_mfma_f32_16x16x32_bf16 v[4:7], v[82:85], v[94:97], v[4:7]
	v_mfma_f32_16x16x32_bf16 v[8:11], v[82:85], v[114:117], v[8:11]
	v_mfma_f32_16x16x32_bf16 v[12:15], v[82:85], v[118:121], v[12:15]
	v_mfma_f32_16x16x32_bf16 v[82:85], v[90:93], v[86:89], v[16:19]
	v_mfma_f32_16x16x32_bf16 v[20:23], v[90:93], v[94:97], v[20:23]
	v_mfma_f32_16x16x32_bf16 v[24:27], v[90:93], v[114:117], v[24:27]
	v_mfma_f32_16x16x32_bf16 v[28:31], v[90:93], v[118:121], v[28:31]
	ds_read_b128 v[16:19], v64 offset:36864
	ds_read_b128 v[90:93], v64 offset:38912
	s_waitcnt lgkmcnt(0)
	v_mfma_f32_16x16x32_bf16 v[122:125], v[16:19], v[86:89], v[32:35]
	v_mfma_f32_16x16x32_bf16 v[36:39], v[16:19], v[94:97], v[36:39]
	v_mfma_f32_16x16x32_bf16 v[40:43], v[16:19], v[114:117], v[40:43]
	v_mfma_f32_16x16x32_bf16 v[44:47], v[16:19], v[118:121], v[44:47]
	ds_read_b128 v[16:19], v112 offset:32768
	v_mfma_f32_16x16x32_bf16 v[86:89], v[90:93], v[86:89], v[48:51]
	v_mfma_f32_16x16x32_bf16 v[52:55], v[90:93], v[94:97], v[52:55]
	v_mfma_f32_16x16x32_bf16 v[56:59], v[90:93], v[114:117], v[56:59]
	v_mfma_f32_16x16x32_bf16 v[60:63], v[90:93], v[118:121], v[60:63]
	ds_read_b128 v[90:93], v113 offset:49152
	ds_read_b128 v[32:35], v112 offset:34816
	ds_read_b128 v[94:97], v113 offset:51200
	ds_read_b128 v[114:117], v113 offset:53248
	ds_read_b128 v[118:121], v113 offset:55296
	s_waitcnt lgkmcnt(0)
	v_mfma_f32_16x16x32_bf16 v[0:3], v[16:19], v[90:93], v[0:3]
	v_mfma_f32_16x16x32_bf16 v[4:7], v[16:19], v[94:97], v[4:7]
	v_mfma_f32_16x16x32_bf16 v[8:11], v[16:19], v[114:117], v[8:11]
	v_mfma_f32_16x16x32_bf16 v[16:19], v[16:19], v[118:121], v[12:15]
	v_mfma_f32_16x16x32_bf16 v[12:15], v[32:35], v[90:93], v[82:85]
	ds_read_b128 v[48:51], v112 offset:36864
	s_nop 1
	ds_read_b128 v[82:85], v112 offset:38912
	s_waitcnt vmcnt(0) lgkmcnt(0)
	s_barrier
	s_cbranch_vccnz .Lge1_exit1
	s_setprio 1
	v_mfma_f32_16x16x32_bf16 v[20:23], v[32:35], v[94:97], v[20:23]
	s_add_i32 m0, s69, 0x8000
	v_lshl_add_u64 v[246:247], s[4:5], 0, v[66:67]
	v_lshl_add_u64 v[246:247], v[246:247], 0, s[16:17]
	global_load_lds_dwordx4 v[246:247], off
	v_mfma_f32_16x16x32_bf16 v[24:27], v[32:35], v[114:117], v[24:27]
	s_add_i32 m0, s69, 0xc000
	v_lshl_add_u64 v[246:247], s[4:5], 0, v[74:75]
	v_lshl_add_u64 v[246:247], v[246:247], 0, s[18:19]
	global_load_lds_dwordx4 v[246:247], off
	v_mfma_f32_16x16x32_bf16 v[32:35], v[32:35], v[118:121], v[28:31]
	s_add_i32 m0, s69, 0x8400
	v_lshl_add_u64 v[246:247], s[4:5], 0, v[68:69]
	v_lshl_add_u64 v[246:247], v[246:247], 0, s[16:17]
	global_load_lds_dwordx4 v[246:247], off
	s_waitcnt lgkmcnt(0)
	v_mfma_f32_16x16x32_bf16 v[28:31], v[48:51], v[90:93], v[122:125]
	s_add_i32 m0, s69, 0xc400
	v_lshl_add_u64 v[246:247], s[4:5], 0, v[76:77]
	v_lshl_add_u64 v[246:247], v[246:247], 0, s[18:19]
	global_load_lds_dwordx4 v[246:247], off
	v_mfma_f32_16x16x32_bf16 v[36:39], v[48:51], v[94:97], v[36:39]
	s_add_i32 m0, s69, 0x8800
	v_lshl_add_u64 v[246:247], s[4:5], 0, v[70:71]
	v_lshl_add_u64 v[246:247], v[246:247], 0, s[16:17]
	global_load_lds_dwordx4 v[246:247], off
	v_mfma_f32_16x16x32_bf16 v[40:43], v[48:51], v[114:117], v[40:43]
	s_add_i32 m0, s69, 0xc800
	v_lshl_add_u64 v[246:247], s[4:5], 0, v[78:79]
	v_lshl_add_u64 v[246:247], v[246:247], 0, s[18:19]
	global_load_lds_dwordx4 v[246:247], off
	v_mfma_f32_16x16x32_bf16 v[48:51], v[48:51], v[118:121], v[44:47]
	s_add_i32 m0, s75, 0x8000
	v_lshl_add_u64 v[246:247], s[4:5], 0, v[72:73]
	v_lshl_add_u64 v[246:247], v[246:247], 0, s[16:17]
	global_load_lds_dwordx4 v[246:247], off
	v_mfma_f32_16x16x32_bf16 v[44:47], v[82:85], v[90:93], v[86:89]
	s_add_i32 m0, s75, 0xc000
	v_lshl_add_u64 v[246:247], s[4:5], 0, v[80:81]
	v_lshl_add_u64 v[246:247], v[246:247], 0, s[18:19]
	global_load_lds_dwordx4 v[246:247], off
	v_mfma_f32_16x16x32_bf16 v[52:55], v[82:85], v[94:97], v[52:55]
	v_mfma_f32_16x16x32_bf16 v[56:59], v[82:85], v[114:117], v[56:59]
	v_mfma_f32_16x16x32_bf16 v[60:63], v[82:85], v[118:121], v[60:63]
	s_cmpk_gt_u32 s9, 0x37f
	s_setprio 0
	s_branch .Lge1_k0

; #define GBAR() do { asm volatile("s_waitcnt vmcnt(0) lgkmcnt(0)" ::: "memory"); __builtin_amdgcn_s_barrier(); } while (0)
; template <int EPI, bool GUARD>
; DEVI void gemm_tile(const Params& p, const bf16_t* __restrict__ A, int lda, const bf16_t* __restrict__ Bt, int ldb, int K,
;                           int row_base, int row_lo, int row_hi, int tile_n, int layer, int which, char* lds) {
;     ...
;   const int swz = c16 >> 1;
;   int koff[2];
; #pragma unroll
;   for (int ks = 0; ks < 2; ++ks) koff[ks] = ((ks * 4 + q4) ^ swz) << 4;
;   const int arow = (wr * 64 + c16) * 128, brow = 16384 + (wc * 64 + c16) * 128;
;     ...
;   GISSUE(0, 0); GBAR();
;   for (int k0 = 0; k0 < K; k0 += 128) {
;     GISSUE(k0 + 64, 1);
;     KSTEPS(0);
;     GBAR();
;     if (k0 + 128 < K) GISSUE(k0 + 128, 0);
;     KSTEPS(1);
;     GBAR();
;   }
.Lge1_k0:
	ds_read_b128 v[114:117], v64
	ds_read_b128 v[118:121], v111 offset:16384
	ds_read_b128 v[122:125], v64 offset:2048
	ds_read_b128 v[126:129], v111 offset:18432
	ds_read_b128 v[130:133], v111 offset:20480
	ds_read_b128 v[134:137], v111 offset:22528
	s_waitcnt lgkmcnt(0)
	v_mfma_f32_16x16x32_bf16 v[0:3], v[114:117], v[118:121], v[0:3]
	s_cselect_b64 s[6:7], -1, 0
	s_and_b64 vcc, exec, s[6:7]
	v_mfma_f32_16x16x32_bf16 v[4:7], v[114:117], v[126:129], v[4:7]
	v_mfma_f32_16x16x32_bf16 v[8:11], v[114:117], v[130:133], v[8:11]
	v_mfma_f32_16x16x32_bf16 v[16:19], v[114:117], v[134:137], v[16:19]
	v_mfma_f32_16x16x32_bf16 v[114:117], v[122:125], v[118:121], v[12:15]
	v_mfma_f32_16x16x32_bf16 v[20:23], v[122:125], v[126:129], v[20:23]
	v_mfma_f32_16x16x32_bf16 v[24:27], v[122:125], v[130:133], v[24:27]
	v_mfma_f32_16x16x32_bf16 v[32:35], v[122:125], v[134:137], v[32:35]
	ds_read_b128 v[12:15], v64 offset:4096
	ds_read_b128 v[122:125], v64 offset:6144
	s_waitcnt lgkmcnt(0)
	v_mfma_f32_16x16x32_bf16 v[138:141], v[12:15], v[118:121], v[28:31]
	v_mfma_f32_16x16x32_bf16 v[36:39], v[12:15], v[126:129], v[36:39]
	v_mfma_f32_16x16x32_bf16 v[40:43], v[12:15], v[130:133], v[40:43]
	v_mfma_f32_16x16x32_bf16 v[48:51], v[12:15], v[134:137], v[48:51]
	ds_read_b128 v[12:15], v112
	v_mfma_f32_16x16x32_bf16 v[118:121], v[122:125], v[118:121], v[44:47]
	v_mfma_f32_16x16x32_bf16 v[52:55], v[122:125], v[126:129], v[52:55]
	v_mfma_f32_16x16x32_bf16 v[56:59], v[122:125], v[130:133], v[56:59]
	v_mfma_f32_16x16x32_bf16 v[60:63], v[122:125], v[134:137], v[60:63]
	ds_read_b128 v[122:125], v113 offset:16384
	ds_read_b128 v[28:31], v112 offset:2048
	ds_read_b128 v[126:129], v113 offset:18432
	ds_read_b128 v[130:133], v113 offset:20480
	ds_read_b128 v[134:137], v113 offset:22528
	s_waitcnt lgkmcnt(0)
	v_mfma_f32_16x16x32_bf16 v[0:3], v[12:15], v[122:125], v[0:3]
	v_mfma_f32_16x16x32_bf16 v[4:7], v[12:15], v[126:129], v[4:7]
	v_mfma_f32_16x16x32_bf16 v[8:11], v[12:15], v[130:133], v[8:11]
	v_mfma_f32_16x16x32_bf16 v[12:15], v[12:15], v[134:137], v[16:19]
	v_mfma_f32_16x16x32_bf16 v[16:19], v[28:31], v[122:125], v[114:117]
	ds_read_b128 v[44:47], v112 offset:4096
	s_nop 1
	ds_read_b128 v[114:117], v112 offset:6144
	s_waitcnt vmcnt(0) lgkmcnt(0)
	s_barrier
	s_cbranch_vccnz .Lge1_last0
	s_setprio 1
	v_mfma_f32_16x16x32_bf16 v[20:23], v[28:31], v[126:129], v[20:23]
	s_mov_b32 m0, s69
	v_lshl_add_u64 v[246:247], s[4:5], 0, v[66:67]
	v_lshl_add_u64 v[246:247], v[246:247], 0, s[26:27]
	global_load_lds_dwordx4 v[246:247], off
	v_mfma_f32_16x16x32_bf16 v[24:27], v[28:31], v[130:133], v[24:27]
	s_mov_b32 m0, s70
	v_lshl_add_u64 v[246:247], s[4:5], 0, v[74:75]
	v_lshl_add_u64 v[246:247], v[246:247], 0, s[34:35]
	global_load_lds_dwordx4 v[246:247], off
	v_mfma_f32_16x16x32_bf16 v[28:31], v[28:31], v[134:137], v[32:35]
	s_mov_b32 m0, s71
	v_lshl_add_u64 v[246:247], s[4:5], 0, v[68:69]
	v_lshl_add_u64 v[246:247], v[246:247], 0, s[26:27]
	global_load_lds_dwordx4 v[246:247], off
	s_waitcnt lgkmcnt(0)
	v_mfma_f32_16x16x32_bf16 v[32:35], v[44:47], v[122:125], v[138:141]
	s_mov_b32 m0, s72
	v_lshl_add_u64 v[246:247], s[4:5], 0, v[76:77]
	v_lshl_add_u64 v[246:247], v[246:247], 0, s[34:35]
	global_load_lds_dwordx4 v[246:247], off
	v_mfma_f32_16x16x32_bf16 v[36:39], v[44:47], v[126:129], v[36:39]
	s_mov_b32 m0, s73
	v_lshl_add_u64 v[246:247], s[4:5], 0, v[70:71]
	v_lshl_add_u64 v[246:247], v[246:247], 0, s[26:27]
	global_load_lds_dwordx4 v[246:247], off
	v_mfma_f32_16x16x32_bf16 v[40:43], v[44:47], v[130:133], v[40:43]
	s_mov_b32 m0, s74
	v_lshl_add_u64 v[246:247], s[4:5], 0, v[78:79]
	v_lshl_add_u64 v[246:247], v[246:247], 0, s[34:35]
	global_load_lds_dwordx4 v[246:247], off
	v_mfma_f32_16x16x32_bf16 v[44:47], v[44:47], v[134:137], v[48:51]
	s_mov_b32 m0, s75
	v_lshl_add_u64 v[246:247], s[4:5], 0, v[72:73]
	v_lshl_add_u64 v[246:247], v[246:247], 0, s[26:27]
	global_load_lds_dwordx4 v[246:247], off
	v_mfma_f32_16x16x32_bf16 v[48:51], v[114:117], v[122:125], v[118:121]
	s_mov_b32 m0, s76
	v_lshl_add_u64 v[246:247], s[4:5], 0, v[80:81]
	v_lshl_add_u64 v[246:247], v[246:247], 0, s[34:35]
	global_load_lds_dwordx4 v[246:247], off
	v_mfma_f32_16x16x32_bf16 v[52:55], v[114:117], v[126:129], v[52:55]
	v_mfma_f32_16x16x32_bf16 v[56:59], v[114:117], v[130:133], v[56:59]
	v_mfma_f32_16x16x32_bf16 v[60:63], v[114:117], v[134:137], v[60:63]
	s_setprio 0
	s_branch .LBB0_667

; #define GBAR() do { asm volatile("s_waitcnt vmcnt(0) lgkmcnt(0)" ::: "memory"); __builtin_amdgcn_s_barrier(); } while (0)
; template <int EPI, bool GUARD>
; DEVI void gemm_tile(const Params& p, const bf16_t* __restrict__ A, int lda, const bf16_t* __restrict__ Bt, int ldb, int K,
;                           int row_base, int row_lo, int row_hi, int tile_n, int layer, int which, char* lds) {
;     ...
;   const int swz = c16 >> 1;
;   int koff[2];
; #pragma unroll
;   for (int ks = 0; ks < 2; ++ks) koff[ks] = ((ks * 4 + q4) ^ swz) << 4;
;   const int arow = (wr * 64 + c16) * 128, brow = 16384 + (wc * 64 + c16) * 128;
;     ...
;   GISSUE(0, 0); GBAR();
;   for (int k0 = 0; k0 < K; k0 += 128) {
;     GISSUE(k0 + 64, 1);
;     KSTEPS(0);
;     GBAR();
;     if (k0 + 128 < K) GISSUE(k0 + 128, 0);
;     KSTEPS(1);
;     GBAR();
;   }
.LBB0_745:
	ds_read_b128 v[82:85], v64 offset:32768
	ds_read_b128 v[86:89], v107 offset:49152
	ds_read_b128 v[90:93], v64 offset:34816
	ds_read_b128 v[94:97], v107 offset:51200
	ds_read_b128 v[110:113], v107 offset:53248
	ds_read_b128 v[114:117], v107 offset:55296
	s_addk_i32 s62, 0x80
	s_waitcnt lgkmcnt(0)
	v_mfma_f32_16x16x32_bf16 v[0:3], v[82:85], v[86:89], v[0:3]
	s_add_u32 s26, s26, 0x100
	s_addc_u32 s27, s27, 0
	s_andn2_b64 vcc, exec, s[34:35]
	v_mfma_f32_16x16x32_bf16 v[4:7], v[82:85], v[94:97], v[4:7]
	v_mfma_f32_16x16x32_bf16 v[8:11], v[82:85], v[110:113], v[8:11]
	v_mfma_f32_16x16x32_bf16 v[12:15], v[82:85], v[114:117], v[12:15]
	v_mfma_f32_16x16x32_bf16 v[16:19], v[90:93], v[86:89], v[16:19]
	v_mfma_f32_16x16x32_bf16 v[20:23], v[90:93], v[94:97], v[20:23]
	v_mfma_f32_16x16x32_bf16 v[24:27], v[90:93], v[110:113], v[24:27]
	v_mfma_f32_16x16x32_bf16 v[28:31], v[90:93], v[114:117], v[28:31]
	ds_read_b128 v[82:85], v64 offset:36864
	ds_read_b128 v[90:93], v64 offset:38912
	s_waitcnt lgkmcnt(0)
	v_mfma_f32_16x16x32_bf16 v[118:121], v[82:85], v[86:89], v[32:35]
	s_nop 2
	ds_read_b128 v[32:35], v108 offset:32768
	v_mfma_f32_16x16x32_bf16 v[122:125], v[82:85], v[94:97], v[36:39]
	v_mfma_f32_16x16x32_bf16 v[126:129], v[82:85], v[110:113], v[40:43]
	v_mfma_f32_16x16x32_bf16 v[82:85], v[82:85], v[114:117], v[44:47]
	v_mfma_f32_16x16x32_bf16 v[86:89], v[90:93], v[86:89], v[48:51]
	v_mfma_f32_16x16x32_bf16 v[94:97], v[90:93], v[94:97], v[52:55]
	v_mfma_f32_16x16x32_bf16 v[110:113], v[90:93], v[110:113], v[56:59]
	v_mfma_f32_16x16x32_bf16 v[90:93], v[90:93], v[114:117], v[60:63]
	ds_read_b128 v[114:117], v109 offset:49152
	ds_read_b128 v[130:133], v108 offset:34816
	ds_read_b128 v[134:137], v109 offset:51200
	ds_read_b128 v[138:141], v109 offset:53248
	ds_read_b128 v[142:145], v109 offset:55296
	s_waitcnt lgkmcnt(0)
	v_mfma_f32_16x16x32_bf16 v[60:63], v[32:35], v[114:117], v[0:3]
	v_mfma_f32_16x16x32_bf16 v[52:55], v[32:35], v[138:141], v[8:11]
	s_nop 1
	ds_read_b128 v[0:3], v108 offset:36864
	ds_read_b128 v[8:11], v108 offset:38912
	s_waitcnt vmcnt(0) lgkmcnt(0)
	s_barrier
	s_cbranch_vccz .Lge2_exit1
	s_setprio 1
	v_mfma_f32_16x16x32_bf16 v[56:59], v[32:35], v[134:137], v[4:7]
	s_mov_b32 m0, s63
	v_lshl_add_u64 v[246:247], s[26:27], 0, v[66:67]
	v_lshl_add_u64 v[246:247], v[246:247], 0, s[4:5]
	global_load_lds_dwordx4 v[246:247], off
	v_mfma_f32_16x16x32_bf16 v[48:51], v[32:35], v[142:145], v[12:15]
	s_mov_b32 m0, s72
	v_lshl_add_u64 v[246:247], s[26:27], 0, v[74:75]
	v_lshl_add_u64 v[246:247], v[246:247], 0, s[6:7]
	global_load_lds_dwordx4 v[246:247], off
	v_mfma_f32_16x16x32_bf16 v[44:47], v[130:133], v[114:117], v[16:19]
	s_mov_b32 m0, s68
	v_lshl_add_u64 v[246:247], s[26:27], 0, v[68:69]
	v_lshl_add_u64 v[246:247], v[246:247], 0, s[4:5]
	global_load_lds_dwordx4 v[246:247], off
	v_mfma_f32_16x16x32_bf16 v[40:43], v[130:133], v[134:137], v[20:23]
	s_mov_b32 m0, s69
	v_lshl_add_u64 v[246:247], s[26:27], 0, v[76:77]
	v_lshl_add_u64 v[246:247], v[246:247], 0, s[6:7]
	global_load_lds_dwordx4 v[246:247], off
	v_mfma_f32_16x16x32_bf16 v[36:39], v[130:133], v[138:141], v[24:27]
	s_mov_b32 m0, s70
	v_lshl_add_u64 v[246:247], s[26:27], 0, v[70:71]
	v_lshl_add_u64 v[246:247], v[246:247], 0, s[4:5]
	global_load_lds_dwordx4 v[246:247], off
	v_mfma_f32_16x16x32_bf16 v[32:35], v[130:133], v[142:145], v[28:31]
	s_mov_b32 m0, s71
	v_lshl_add_u64 v[246:247], s[26:27], 0, v[78:79]
	v_lshl_add_u64 v[246:247], v[246:247], 0, s[6:7]
	global_load_lds_dwordx4 v[246:247], off
	s_waitcnt lgkmcnt(0)
	v_mfma_f32_16x16x32_bf16 v[28:31], v[0:3], v[114:117], v[118:121]
	s_mov_b32 m0, s73
	v_lshl_add_u64 v[246:247], s[26:27], 0, v[72:73]
	v_lshl_add_u64 v[246:247], v[246:247], 0, s[4:5]
	global_load_lds_dwordx4 v[246:247], off
	v_mfma_f32_16x16x32_bf16 v[24:27], v[0:3], v[134:137], v[122:125]
	s_mov_b32 m0, s74
	v_lshl_add_u64 v[246:247], s[26:27], 0, v[80:81]
	v_lshl_add_u64 v[246:247], v[246:247], 0, s[6:7]
	global_load_lds_dwordx4 v[246:247], off
	v_mfma_f32_16x16x32_bf16 v[16:19], v[0:3], v[138:141], v[126:129]
	v_mfma_f32_16x16x32_bf16 v[12:15], v[0:3], v[142:145], v[82:85]
	v_mfma_f32_16x16x32_bf16 v[4:7], v[8:11], v[114:117], v[86:89]
	v_mfma_f32_16x16x32_bf16 v[0:3], v[8:11], v[134:137], v[94:97]
	v_mfma_f32_16x16x32_bf16 v[20:23], v[8:11], v[138:141], v[110:113]
	v_mfma_f32_16x16x32_bf16 v[8:11], v[8:11], v[142:145], v[90:93]
	s_cmpk_gt_u32 s62, 0xa7f
	s_cselect_b64 s[34:35], -1, 0
	s_and_b64 vcc, exec, s[34:35]
	s_setprio 0
	s_branch .Lge2_k0

; #define GBAR() do { asm volatile("s_waitcnt vmcnt(0) lgkmcnt(0)" ::: "memory"); __builtin_amdgcn_s_barrier(); } while (0)
; template <int EPI, bool GUARD>
; DEVI void gemm_tile(const Params& p, const bf16_t* __restrict__ A, int lda, const bf16_t* __restrict__ Bt, int ldb, int K,
;                           int row_base, int row_lo, int row_hi, int tile_n, int layer, int which, char* lds) {
;     ...
;   const int swz = c16 >> 1;
;   int koff[2];
; #pragma unroll
;   for (int ks = 0; ks < 2; ++ks) koff[ks] = ((ks * 4 + q4) ^ swz) << 4;
;   const int arow = (wr * 64 + c16) * 128, brow = 16384 + (wc * 64 + c16) * 128;
;     ...
;   GISSUE(0, 0); GBAR();
;   for (int k0 = 0; k0 < K; k0 += 128) {
;     GISSUE(k0 + 64, 1);
;     KSTEPS(0);
;     GBAR();
;     if (k0 + 128 < K) GISSUE(k0 + 128, 0);
;     KSTEPS(1);
;     GBAR();
;   }
.Lge2_k0:
	ds_read_b128 v[110:113], v64
	ds_read_b128 v[114:117], v107 offset:16384
	ds_read_b128 v[118:121], v64 offset:2048
	ds_read_b128 v[122:125], v107 offset:18432
	ds_read_b128 v[126:129], v107 offset:20480
	ds_read_b128 v[130:133], v107 offset:22528
	s_waitcnt lgkmcnt(0)
	v_mfma_f32_16x16x32_bf16 v[60:63], v[110:113], v[114:117], v[60:63]
	v_mfma_f32_16x16x32_bf16 v[56:59], v[110:113], v[122:125], v[56:59]
	v_mfma_f32_16x16x32_bf16 v[52:55], v[110:113], v[126:129], v[52:55]
	v_mfma_f32_16x16x32_bf16 v[48:51], v[110:113], v[130:133], v[48:51]
	v_mfma_f32_16x16x32_bf16 v[44:47], v[118:121], v[114:117], v[44:47]
	v_mfma_f32_16x16x32_bf16 v[40:43], v[118:121], v[122:125], v[40:43]
	v_mfma_f32_16x16x32_bf16 v[36:39], v[118:121], v[126:129], v[36:39]
	v_mfma_f32_16x16x32_bf16 v[32:35], v[118:121], v[130:133], v[32:35]
	ds_read_b128 v[110:113], v64 offset:4096
	ds_read_b128 v[118:121], v64 offset:6144
	s_waitcnt lgkmcnt(0)
	v_mfma_f32_16x16x32_bf16 v[134:137], v[110:113], v[114:117], v[28:31]
	v_mfma_f32_16x16x32_bf16 v[138:141], v[110:113], v[122:125], v[24:27]
	v_mfma_f32_16x16x32_bf16 v[142:145], v[110:113], v[126:129], v[16:19]
	v_mfma_f32_16x16x32_bf16 v[110:113], v[110:113], v[130:133], v[12:15]
	s_nop 2
	ds_read_b128 v[12:15], v108
	v_mfma_f32_16x16x32_bf16 v[114:117], v[118:121], v[114:117], v[4:7]
	v_mfma_f32_16x16x32_bf16 v[122:125], v[118:121], v[122:125], v[0:3]
	v_mfma_f32_16x16x32_bf16 v[126:129], v[118:121], v[126:129], v[20:23]
	v_mfma_f32_16x16x32_bf16 v[118:121], v[118:121], v[130:133], v[8:11]
	ds_read_b128 v[130:133], v109 offset:16384
	ds_read_b128 v[28:31], v108 offset:2048
	ds_read_b128 v[146:149], v109 offset:18432
	s_waitcnt lgkmcnt(0)
	v_mfma_f32_16x16x32_bf16 v[0:3], v[12:15], v[130:133], v[60:63]
	v_mfma_f32_16x16x32_bf16 v[4:7], v[12:15], v[146:149], v[56:59]
	s_nop 2
	ds_read_b128 v[56:59], v109 offset:20480
	ds_read_b128 v[60:63], v109 offset:22528
	v_mfma_f32_16x16x32_bf16 v[16:19], v[28:31], v[130:133], v[44:47]
	s_nop 2
	ds_read_b128 v[44:47], v108 offset:4096
	ds_read_b128 v[150:153], v108 offset:6144
	s_waitcnt vmcnt(0) lgkmcnt(0)
	s_barrier
	s_cbranch_vccnz .Lge2_last0
	s_setprio 1
	s_waitcnt lgkmcnt(0)
	v_mfma_f32_16x16x32_bf16 v[8:11], v[12:15], v[56:59], v[52:55]
	s_mov_b32 m0, s54
	v_lshl_add_u64 v[246:247], s[26:27], 0, v[66:67]
	v_lshl_add_u64 v[246:247], v[246:247], 0, s[8:9]
	global_load_lds_dwordx4 v[246:247], off
	v_mfma_f32_16x16x32_bf16 v[12:15], v[12:15], v[60:63], v[48:51]
	s_mov_b32 m0, s55
	v_lshl_add_u64 v[246:247], s[26:27], 0, v[74:75]
	v_lshl_add_u64 v[246:247], v[246:247], 0, s[16:17]
	global_load_lds_dwordx4 v[246:247], off
	v_mfma_f32_16x16x32_bf16 v[20:23], v[28:31], v[146:149], v[40:43]
	s_mov_b32 m0, s56
	v_lshl_add_u64 v[246:247], s[26:27], 0, v[68:69]
	v_lshl_add_u64 v[246:247], v[246:247], 0, s[8:9]
	global_load_lds_dwordx4 v[246:247], off
	v_mfma_f32_16x16x32_bf16 v[24:27], v[28:31], v[56:59], v[36:39]
	s_mov_b32 m0, s57
	v_lshl_add_u64 v[246:247], s[26:27], 0, v[76:77]
	v_lshl_add_u64 v[246:247], v[246:247], 0, s[16:17]
	global_load_lds_dwordx4 v[246:247], off
	v_mfma_f32_16x16x32_bf16 v[28:31], v[28:31], v[60:63], v[32:35]
	s_mov_b32 m0, s58
	v_lshl_add_u64 v[246:247], s[26:27], 0, v[70:71]
	v_lshl_add_u64 v[246:247], v[246:247], 0, s[8:9]
	global_load_lds_dwordx4 v[246:247], off
	v_mfma_f32_16x16x32_bf16 v[32:35], v[44:47], v[130:133], v[134:137]
	s_mov_b32 m0, s59
	v_lshl_add_u64 v[246:247], s[26:27], 0, v[78:79]
	v_lshl_add_u64 v[246:247], v[246:247], 0, s[16:17]
	global_load_lds_dwordx4 v[246:247], off
	v_mfma_f32_16x16x32_bf16 v[36:39], v[44:47], v[146:149], v[138:141]
	s_mov_b32 m0, s60
	v_lshl_add_u64 v[246:247], s[26:27], 0, v[72:73]
	v_lshl_add_u64 v[246:247], v[246:247], 0, s[8:9]
	global_load_lds_dwordx4 v[246:247], off
	v_mfma_f32_16x16x32_bf16 v[40:43], v[44:47], v[56:59], v[142:145]
	s_mov_b32 m0, s61
	v_lshl_add_u64 v[246:247], s[26:27], 0, v[80:81]
	v_lshl_add_u64 v[246:247], v[246:247], 0, s[16:17]
	global_load_lds_dwordx4 v[246:247], off
	v_mfma_f32_16x16x32_bf16 v[44:47], v[44:47], v[60:63], v[110:113]
	v_mfma_f32_16x16x32_bf16 v[48:51], v[150:153], v[130:133], v[114:117]
	v_mfma_f32_16x16x32_bf16 v[52:55], v[150:153], v[146:149], v[122:125]
	v_mfma_f32_16x16x32_bf16 v[56:59], v[150:153], v[56:59], v[126:129]
	v_mfma_f32_16x16x32_bf16 v[60:63], v[150:153], v[60:63], v[118:121]
	s_setprio 0
	s_branch .LBB0_745

; #define GBAR() do { asm volatile("s_waitcnt vmcnt(0) lgkmcnt(0)" ::: "memory"); __builtin_amdgcn_s_barrier(); } while (0)
; template <int EPI, bool GUARD>
; DEVI void gemm_tile(const Params& p, const bf16_t* __restrict__ A, int lda, const bf16_t* __restrict__ Bt, int ldb, int K,
;                           int row_base, int row_lo, int row_hi, int tile_n, int layer, int which, char* lds) {
;     ...
;   const int swz = c16 >> 1;
;   int koff[2];
; #pragma unroll
;   for (int ks = 0; ks < 2; ++ks) koff[ks] = ((ks * 4 + q4) ^ swz) << 4;
;   const int arow = (wr * 64 + c16) * 128, brow = 16384 + (wc * 64 + c16) * 128;
;     ...
;   GISSUE(0, 0); GBAR();
;   for (int k0 = 0; k0 < K; k0 += 128) {
;     GISSUE(k0 + 64, 1);
;     KSTEPS(0);
;     GBAR();
;     if (k0 + 128 < K) GISSUE(k0 + 128, 0);
;     KSTEPS(1);
;     GBAR();
;   }
.LBB0_878:
	ds_read_b128 v[80:83], v101 offset:32768
	ds_read_b128 v[84:87], v102 offset:49152
	ds_read_b128 v[88:91], v101 offset:34816
	ds_read_b128 v[92:95], v102 offset:51200
	ds_read_b128 v[106:109], v102 offset:53248
	ds_read_b128 v[110:113], v102 offset:55296
	s_addk_i32 s85, 0x80
	s_waitcnt lgkmcnt(0)
	v_mfma_f32_16x16x32_bf16 v[0:3], v[80:83], v[84:87], v[0:3]
	s_add_u32 s4, s4, 0x100
	s_addc_u32 s5, s5, 0
	s_and_b64 vcc, exec, s[52:53]
	v_mfma_f32_16x16x32_bf16 v[4:7], v[80:83], v[92:95], v[4:7]
	v_mfma_f32_16x16x32_bf16 v[8:11], v[80:83], v[106:109], v[8:11]
	v_mfma_f32_16x16x32_bf16 v[12:15], v[80:83], v[110:113], v[12:15]
	v_mfma_f32_16x16x32_bf16 v[80:83], v[88:91], v[84:87], v[16:19]
	v_mfma_f32_16x16x32_bf16 v[20:23], v[88:91], v[92:95], v[20:23]
	v_mfma_f32_16x16x32_bf16 v[24:27], v[88:91], v[106:109], v[24:27]
	v_mfma_f32_16x16x32_bf16 v[28:31], v[88:91], v[110:113], v[28:31]
	ds_read_b128 v[16:19], v101 offset:36864
	ds_read_b128 v[88:91], v101 offset:38912
	s_waitcnt lgkmcnt(0)
	v_mfma_f32_16x16x32_bf16 v[114:117], v[16:19], v[84:87], v[32:35]
	v_mfma_f32_16x16x32_bf16 v[36:39], v[16:19], v[92:95], v[36:39]
	v_mfma_f32_16x16x32_bf16 v[40:43], v[16:19], v[106:109], v[40:43]
	v_mfma_f32_16x16x32_bf16 v[44:47], v[16:19], v[110:113], v[44:47]
	ds_read_b128 v[16:19], v103 offset:32768
	v_mfma_f32_16x16x32_bf16 v[84:87], v[88:91], v[84:87], v[48:51]
	v_mfma_f32_16x16x32_bf16 v[52:55], v[88:91], v[92:95], v[52:55]
	v_mfma_f32_16x16x32_bf16 v[56:59], v[88:91], v[106:109], v[56:59]
	v_mfma_f32_16x16x32_bf16 v[60:63], v[88:91], v[110:113], v[60:63]
	ds_read_b128 v[88:91], v104 offset:49152
	ds_read_b128 v[32:35], v103 offset:34816
	ds_read_b128 v[92:95], v104 offset:51200
	ds_read_b128 v[106:109], v104 offset:53248
	ds_read_b128 v[110:113], v104 offset:55296
	s_waitcnt lgkmcnt(0)
	v_mfma_f32_16x16x32_bf16 v[0:3], v[16:19], v[88:91], v[0:3]
	v_mfma_f32_16x16x32_bf16 v[4:7], v[16:19], v[92:95], v[4:7]
	v_mfma_f32_16x16x32_bf16 v[8:11], v[16:19], v[106:109], v[8:11]
	v_mfma_f32_16x16x32_bf16 v[16:19], v[16:19], v[110:113], v[12:15]
	v_mfma_f32_16x16x32_bf16 v[12:15], v[32:35], v[88:91], v[80:83]
	ds_read_b128 v[48:51], v103 offset:36864
	s_nop 1
	ds_read_b128 v[80:83], v103 offset:38912
	s_waitcnt vmcnt(0) lgkmcnt(0)
	s_barrier
	s_cbranch_vccnz .Lge3_exit1
	s_setprio 1
	v_mfma_f32_16x16x32_bf16 v[20:23], v[32:35], v[92:95], v[20:23]
	s_add_i32 m0, s72, 0x8000
	v_lshl_add_u64 v[246:247], s[4:5], 0, v[64:65]
	v_lshl_add_u64 v[246:247], v[246:247], 0, s[16:17]
	global_load_lds_dwordx4 v[246:247], off
	v_mfma_f32_16x16x32_bf16 v[24:27], v[32:35], v[106:109], v[24:27]
	s_add_i32 m0, s72, 0xc000
	v_lshl_add_u64 v[246:247], s[4:5], 0, v[72:73]
	v_lshl_add_u64 v[246:247], v[246:247], 0, s[18:19]
	global_load_lds_dwordx4 v[246:247], off
	v_mfma_f32_16x16x32_bf16 v[32:35], v[32:35], v[110:113], v[28:31]
	s_add_i32 m0, s72, 0x8400
	v_lshl_add_u64 v[246:247], s[4:5], 0, v[66:67]
	v_lshl_add_u64 v[246:247], v[246:247], 0, s[16:17]
	global_load_lds_dwordx4 v[246:247], off
	s_waitcnt lgkmcnt(0)
	v_mfma_f32_16x16x32_bf16 v[28:31], v[48:51], v[88:91], v[114:117]
	s_add_i32 m0, s72, 0xc400
	v_lshl_add_u64 v[246:247], s[4:5], 0, v[74:75]
	v_lshl_add_u64 v[246:247], v[246:247], 0, s[18:19]
	global_load_lds_dwordx4 v[246:247], off
	v_mfma_f32_16x16x32_bf16 v[36:39], v[48:51], v[92:95], v[36:39]
	s_add_i32 m0, s72, 0x8800
	v_lshl_add_u64 v[246:247], s[4:5], 0, v[68:69]
	v_lshl_add_u64 v[246:247], v[246:247], 0, s[16:17]
	global_load_lds_dwordx4 v[246:247], off
	v_mfma_f32_16x16x32_bf16 v[40:43], v[48:51], v[106:109], v[40:43]
	s_add_i32 m0, s72, 0xc800
	v_lshl_add_u64 v[246:247], s[4:5], 0, v[76:77]
	v_lshl_add_u64 v[246:247], v[246:247], 0, s[18:19]
	global_load_lds_dwordx4 v[246:247], off
	v_mfma_f32_16x16x32_bf16 v[48:51], v[48:51], v[110:113], v[44:47]
	s_add_i32 m0, s78, 0x8000
	v_lshl_add_u64 v[246:247], s[4:5], 0, v[70:71]
	v_lshl_add_u64 v[246:247], v[246:247], 0, s[16:17]
	global_load_lds_dwordx4 v[246:247], off
	v_mfma_f32_16x16x32_bf16 v[44:47], v[80:83], v[88:91], v[84:87]
	s_add_i32 m0, s78, 0xc000
	v_lshl_add_u64 v[246:247], s[4:5], 0, v[78:79]
	v_lshl_add_u64 v[246:247], v[246:247], 0, s[18:19]
	global_load_lds_dwordx4 v[246:247], off
	v_mfma_f32_16x16x32_bf16 v[52:55], v[80:83], v[92:95], v[52:55]
	v_mfma_f32_16x16x32_bf16 v[56:59], v[80:83], v[106:109], v[56:59]
	v_mfma_f32_16x16x32_bf16 v[60:63], v[80:83], v[110:113], v[60:63]
	s_cmpk_gt_u32 s85, 0x37f
	s_setprio 0
	s_branch .Lge3_k0

; #define GBAR() do { asm volatile("s_waitcnt vmcnt(0) lgkmcnt(0)" ::: "memory"); __builtin_amdgcn_s_barrier(); } while (0)
; template <int EPI, bool GUARD>
; DEVI void gemm_tile(const Params& p, const bf16_t* __restrict__ A, int lda, const bf16_t* __restrict__ Bt, int ldb, int K,
;                           int row_base, int row_lo, int row_hi, int tile_n, int layer, int which, char* lds) {
;     ...
;   const int swz = c16 >> 1;
;   int koff[2];
; #pragma unroll
;   for (int ks = 0; ks < 2; ++ks) koff[ks] = ((ks * 4 + q4) ^ swz) << 4;
;   const int arow = (wr * 64 + c16) * 128, brow = 16384 + (wc * 64 + c16) * 128;
;     ...
;   GISSUE(0, 0); GBAR();
;   for (int k0 = 0; k0 < K; k0 += 128) {
;     GISSUE(k0 + 64, 1);
;     KSTEPS(0);
;     GBAR();
;     if (k0 + 128 < K) GISSUE(k0 + 128, 0);
;     KSTEPS(1);
;     GBAR();
;   }
.Lge3_k0:
	ds_read_b128 v[106:109], v101
	ds_read_b128 v[110:113], v102 offset:16384
	ds_read_b128 v[114:117], v101 offset:2048
	ds_read_b128 v[118:121], v102 offset:18432
	ds_read_b128 v[122:125], v102 offset:20480
	ds_read_b128 v[130:133], v102 offset:22528
	s_waitcnt lgkmcnt(0)
	v_mfma_f32_16x16x32_bf16 v[0:3], v[106:109], v[110:113], v[0:3]
	s_cselect_b64 s[52:53], -1, 0
	s_and_b64 vcc, exec, s[52:53]
	v_mfma_f32_16x16x32_bf16 v[4:7], v[106:109], v[118:121], v[4:7]
	v_mfma_f32_16x16x32_bf16 v[8:11], v[106:109], v[122:125], v[8:11]
	v_mfma_f32_16x16x32_bf16 v[16:19], v[106:109], v[130:133], v[16:19]
	v_mfma_f32_16x16x32_bf16 v[106:109], v[114:117], v[110:113], v[12:15]
	v_mfma_f32_16x16x32_bf16 v[20:23], v[114:117], v[118:121], v[20:23]
	v_mfma_f32_16x16x32_bf16 v[24:27], v[114:117], v[122:125], v[24:27]
	v_mfma_f32_16x16x32_bf16 v[32:35], v[114:117], v[130:133], v[32:35]
	ds_read_b128 v[12:15], v101 offset:4096
	ds_read_b128 v[114:117], v101 offset:6144
	s_waitcnt lgkmcnt(0)
	v_mfma_f32_16x16x32_bf16 v[140:143], v[12:15], v[110:113], v[28:31]
	v_mfma_f32_16x16x32_bf16 v[36:39], v[12:15], v[118:121], v[36:39]
	v_mfma_f32_16x16x32_bf16 v[40:43], v[12:15], v[122:125], v[40:43]
	v_mfma_f32_16x16x32_bf16 v[48:51], v[12:15], v[130:133], v[48:51]
	ds_read_b128 v[12:15], v103
	v_mfma_f32_16x16x32_bf16 v[110:113], v[114:117], v[110:113], v[44:47]
	v_mfma_f32_16x16x32_bf16 v[52:55], v[114:117], v[118:121], v[52:55]
	v_mfma_f32_16x16x32_bf16 v[56:59], v[114:117], v[122:125], v[56:59]
	v_mfma_f32_16x16x32_bf16 v[60:63], v[114:117], v[130:133], v[60:63]
	ds_read_b128 v[114:117], v104 offset:16384
	ds_read_b128 v[28:31], v103 offset:2048
	ds_read_b128 v[118:121], v104 offset:18432
	ds_read_b128 v[122:125], v104 offset:20480
	ds_read_b128 v[130:133], v104 offset:22528
	s_waitcnt lgkmcnt(0)
	v_mfma_f32_16x16x32_bf16 v[0:3], v[12:15], v[114:117], v[0:3]
	v_mfma_f32_16x16x32_bf16 v[4:7], v[12:15], v[118:121], v[4:7]
	v_mfma_f32_16x16x32_bf16 v[8:11], v[12:15], v[122:125], v[8:11]
	v_mfma_f32_16x16x32_bf16 v[12:15], v[12:15], v[130:133], v[16:19]
	v_mfma_f32_16x16x32_bf16 v[16:19], v[28:31], v[114:117], v[106:109]
	ds_read_b128 v[44:47], v103 offset:4096
	s_nop 1
	ds_read_b128 v[106:109], v103 offset:6144
	s_waitcnt vmcnt(0) lgkmcnt(0)
	s_barrier
	s_cbranch_vccnz .Lge3_last0
	s_setprio 1
	v_mfma_f32_16x16x32_bf16 v[20:23], v[28:31], v[118:121], v[20:23]
	s_mov_b32 m0, s72
	v_lshl_add_u64 v[246:247], s[4:5], 0, v[64:65]
	v_lshl_add_u64 v[246:247], v[246:247], 0, s[26:27]
	global_load_lds_dwordx4 v[246:247], off
	v_mfma_f32_16x16x32_bf16 v[24:27], v[28:31], v[122:125], v[24:27]
	s_mov_b32 m0, s73
	v_lshl_add_u64 v[246:247], s[4:5], 0, v[72:73]
	v_lshl_add_u64 v[246:247], v[246:247], 0, s[34:35]
	global_load_lds_dwordx4 v[246:247], off
	v_mfma_f32_16x16x32_bf16 v[28:31], v[28:31], v[130:133], v[32:35]
	s_mov_b32 m0, s74
	v_lshl_add_u64 v[246:247], s[4:5], 0, v[66:67]
	v_lshl_add_u64 v[246:247], v[246:247], 0, s[26:27]
	global_load_lds_dwordx4 v[246:247], off
	s_waitcnt lgkmcnt(0)
	v_mfma_f32_16x16x32_bf16 v[32:35], v[44:47], v[114:117], v[140:143]
	s_mov_b32 m0, s75
	v_lshl_add_u64 v[246:247], s[4:5], 0, v[74:75]
	v_lshl_add_u64 v[246:247], v[246:247], 0, s[34:35]
	global_load_lds_dwordx4 v[246:247], off
	v_mfma_f32_16x16x32_bf16 v[36:39], v[44:47], v[118:121], v[36:39]
	s_mov_b32 m0, s76
	v_lshl_add_u64 v[246:247], s[4:5], 0, v[68:69]
	v_lshl_add_u64 v[246:247], v[246:247], 0, s[26:27]
	global_load_lds_dwordx4 v[246:247], off
	v_mfma_f32_16x16x32_bf16 v[40:43], v[44:47], v[122:125], v[40:43]
	s_mov_b32 m0, s77
	v_lshl_add_u64 v[246:247], s[4:5], 0, v[76:77]
	v_lshl_add_u64 v[246:247], v[246:247], 0, s[34:35]
	global_load_lds_dwordx4 v[246:247], off
	v_mfma_f32_16x16x32_bf16 v[44:47], v[44:47], v[130:133], v[48:51]
	s_mov_b32 m0, s78
	v_lshl_add_u64 v[246:247], s[4:5], 0, v[70:71]
	v_lshl_add_u64 v[246:247], v[246:247], 0, s[26:27]
	global_load_lds_dwordx4 v[246:247], off
	v_mfma_f32_16x16x32_bf16 v[48:51], v[106:109], v[114:117], v[110:113]
	s_mov_b32 m0, s79
	v_lshl_add_u64 v[246:247], s[4:5], 0, v[78:79]
	v_lshl_add_u64 v[246:247], v[246:247], 0, s[34:35]
	global_load_lds_dwordx4 v[246:247], off
	v_mfma_f32_16x16x32_bf16 v[52:55], v[106:109], v[118:121], v[52:55]
	v_mfma_f32_16x16x32_bf16 v[56:59], v[106:109], v[122:125], v[56:59]
	v_mfma_f32_16x16x32_bf16 v[60:63], v[106:109], v[130:133], v[60:63]
	s_setprio 0
	s_branch .LBB0_878

; #define GBAR() do { asm volatile("s_waitcnt vmcnt(0) lgkmcnt(0)" ::: "memory"); __builtin_amdgcn_s_barrier(); } while (0)
; template <int EPI, bool GUARD>
; DEVI void gemm_tile(const Params& p, const bf16_t* __restrict__ A, int lda, const bf16_t* __restrict__ Bt, int ldb, int K,
;                           int row_base, int row_lo, int row_hi, int tile_n, int layer, int which, char* lds) {
;     ...
;   const int swz = c16 >> 1;
;   int koff[2];
; #pragma unroll
;   for (int ks = 0; ks < 2; ++ks) koff[ks] = ((ks * 4 + q4) ^ swz) << 4;
;   const int arow = (wr * 64 + c16) * 128, brow = 16384 + (wc * 64 + c16) * 128;
;     ...
;   GISSUE(0, 0); GBAR();
;   for (int k0 = 0; k0 < K; k0 += 128) {
;     GISSUE(k0 + 64, 1);
;     KSTEPS(0);
;     GBAR();
;     if (k0 + 128 < K) GISSUE(k0 + 128, 0);
;     KSTEPS(1);
;     GBAR();
;   }
.LBB0_959:
	ds_read_b128 v[82:85], v64 offset:32768
	ds_read_b128 v[86:89], v103 offset:49152
	ds_read_b128 v[90:93], v64 offset:34816
	ds_read_b128 v[94:97], v103 offset:51200
	ds_read_b128 v[106:109], v103 offset:53248
	ds_read_b128 v[110:113], v103 offset:55296
	s_addk_i32 s69, 0x80
	s_waitcnt lgkmcnt(0)
	v_mfma_f32_16x16x32_bf16 v[0:3], v[82:85], v[86:89], v[0:3]
	s_add_u32 s34, s34, 0x100
	s_addc_u32 s35, s35, 0
	s_and_b64 vcc, exec, s[44:45]
	v_mfma_f32_16x16x32_bf16 v[4:7], v[82:85], v[94:97], v[4:7]
	v_mfma_f32_16x16x32_bf16 v[8:11], v[82:85], v[106:109], v[8:11]
	v_mfma_f32_16x16x32_bf16 v[82:85], v[82:85], v[110:113], v[12:15]
	v_mfma_f32_16x16x32_bf16 v[16:19], v[90:93], v[86:89], v[16:19]
	v_mfma_f32_16x16x32_bf16 v[20:23], v[90:93], v[94:97], v[20:23]
	v_mfma_f32_16x16x32_bf16 v[24:27], v[90:93], v[106:109], v[24:27]
	v_mfma_f32_16x16x32_bf16 v[28:31], v[90:93], v[110:113], v[28:31]
	ds_read_b128 v[12:15], v64 offset:36864
	ds_read_b128 v[90:93], v64 offset:38912
	s_waitcnt lgkmcnt(0)
	v_mfma_f32_16x16x32_bf16 v[114:117], v[12:15], v[94:97], v[36:39]
	v_mfma_f32_16x16x32_bf16 v[52:55], v[90:93], v[94:97], v[52:55]
	ds_read_b128 v[94:97], v104 offset:32768
	v_mfma_f32_16x16x32_bf16 v[32:35], v[12:15], v[86:89], v[32:35]
	v_mfma_f32_16x16x32_bf16 v[40:43], v[12:15], v[106:109], v[40:43]
	v_mfma_f32_16x16x32_bf16 v[44:47], v[12:15], v[110:113], v[44:47]
	v_mfma_f32_16x16x32_bf16 v[86:89], v[90:93], v[86:89], v[48:51]
	v_mfma_f32_16x16x32_bf16 v[56:59], v[90:93], v[106:109], v[56:59]
	v_mfma_f32_16x16x32_bf16 v[60:63], v[90:93], v[110:113], v[60:63]
	ds_read_b128 v[90:93], v105 offset:49152
	ds_read_b128 v[106:109], v104 offset:34816
	ds_read_b128 v[110:113], v105 offset:51200
	ds_read_b128 v[118:121], v105 offset:53248
	ds_read_b128 v[128:131], v105 offset:55296
	s_waitcnt lgkmcnt(0)
	v_mfma_f32_16x16x32_bf16 v[48:51], v[94:97], v[90:93], v[0:3]
	v_mfma_f32_16x16x32_bf16 v[36:39], v[94:97], v[110:113], v[4:7]
	v_mfma_f32_16x16x32_bf16 v[12:15], v[94:97], v[118:121], v[8:11]
	v_mfma_f32_16x16x32_bf16 v[8:11], v[94:97], v[128:131], v[82:85]
	s_nop 2
	ds_read_b128 v[82:85], v104 offset:36864
	ds_read_b128 v[94:97], v104 offset:38912
	s_waitcnt vmcnt(0) lgkmcnt(0)
	s_barrier
	s_cbranch_vccnz .Lge4_exit1
	s_setprio 1
	v_mfma_f32_16x16x32_bf16 v[4:7], v[106:109], v[90:93], v[16:19]
	s_add_i32 m0, s59, 0x8000
	v_lshl_add_u64 v[246:247], s[34:35], 0, v[66:67]
	v_lshl_add_u64 v[246:247], v[246:247], 0, s[4:5]
	global_load_lds_dwordx4 v[246:247], off
	v_mfma_f32_16x16x32_bf16 v[0:3], v[106:109], v[110:113], v[20:23]
	s_add_i32 m0, s59, 0xc000
	v_lshl_add_u64 v[246:247], s[34:35], 0, v[74:75]
	v_lshl_add_u64 v[246:247], v[246:247], 0, s[16:17]
	global_load_lds_dwordx4 v[246:247], off
	v_mfma_f32_16x16x32_bf16 v[16:19], v[106:109], v[118:121], v[24:27]
	s_add_i32 m0, s59, 0x8400
	v_lshl_add_u64 v[246:247], s[34:35], 0, v[68:69]
	v_lshl_add_u64 v[246:247], v[246:247], 0, s[4:5]
	global_load_lds_dwordx4 v[246:247], off
	v_mfma_f32_16x16x32_bf16 v[24:27], v[106:109], v[128:131], v[28:31]
	s_add_i32 m0, s59, 0xc400
	v_lshl_add_u64 v[246:247], s[34:35], 0, v[76:77]
	v_lshl_add_u64 v[246:247], v[246:247], 0, s[16:17]
	global_load_lds_dwordx4 v[246:247], off
	s_waitcnt lgkmcnt(0)
	v_mfma_f32_16x16x32_bf16 v[20:23], v[82:85], v[90:93], v[32:35]
	s_add_i32 m0, s59, 0x8800
	v_lshl_add_u64 v[246:247], s[34:35], 0, v[70:71]
	v_lshl_add_u64 v[246:247], v[246:247], 0, s[4:5]
	global_load_lds_dwordx4 v[246:247], off
	v_mfma_f32_16x16x32_bf16 v[28:31], v[82:85], v[110:113], v[114:117]
	s_add_i32 m0, s59, 0xc800
	v_lshl_add_u64 v[246:247], s[34:35], 0, v[78:79]
	v_lshl_add_u64 v[246:247], v[246:247], 0, s[16:17]
	global_load_lds_dwordx4 v[246:247], off
	v_mfma_f32_16x16x32_bf16 v[32:35], v[82:85], v[118:121], v[40:43]
	s_add_i32 m0, s65, 0x8000
	v_lshl_add_u64 v[246:247], s[34:35], 0, v[72:73]
	v_lshl_add_u64 v[246:247], v[246:247], 0, s[4:5]
	global_load_lds_dwordx4 v[246:247], off
	v_mfma_f32_16x16x32_bf16 v[44:47], v[82:85], v[128:131], v[44:47]
	s_add_i32 m0, s65, 0xc000
	v_lshl_add_u64 v[246:247], s[34:35], 0, v[80:81]
	v_lshl_add_u64 v[246:247], v[246:247], 0, s[16:17]
	global_load_lds_dwordx4 v[246:247], off
	v_mfma_f32_16x16x32_bf16 v[40:43], v[94:97], v[90:93], v[86:89]
	v_mfma_f32_16x16x32_bf16 v[52:55], v[94:97], v[110:113], v[52:55]
	v_mfma_f32_16x16x32_bf16 v[56:59], v[94:97], v[118:121], v[56:59]
	v_mfma_f32_16x16x32_bf16 v[60:63], v[94:97], v[128:131], v[60:63]
	s_cmpk_gt_u32 s69, 0x27f
	s_setprio 0
	s_branch .Lge4_k0

; #define GBAR() do { asm volatile("s_waitcnt vmcnt(0) lgkmcnt(0)" ::: "memory"); __builtin_amdgcn_s_barrier(); } while (0)
; template <int EPI, bool GUARD>
; DEVI void gemm_tile(const Params& p, const bf16_t* __restrict__ A, int lda, const bf16_t* __restrict__ Bt, int ldb, int K,
;                           int row_base, int row_lo, int row_hi, int tile_n, int layer, int which, char* lds) {
;     ...
;   const int swz = c16 >> 1;
;   int koff[2];
; #pragma unroll
;   for (int ks = 0; ks < 2; ++ks) koff[ks] = ((ks * 4 + q4) ^ swz) << 4;
;   const int arow = (wr * 64 + c16) * 128, brow = 16384 + (wc * 64 + c16) * 128;
;     ...
;   GISSUE(0, 0); GBAR();
;   for (int k0 = 0; k0 < K; k0 += 128) {
;     GISSUE(k0 + 64, 1);
;     KSTEPS(0);
;     GBAR();
;     if (k0 + 128 < K) GISSUE(k0 + 128, 0);
;     KSTEPS(1);
;     GBAR();
;   }
.Lge4_k0:
	ds_read_b128 v[106:109], v64
	ds_read_b128 v[110:113], v103 offset:16384
	ds_read_b128 v[114:117], v64 offset:2048
	ds_read_b128 v[118:121], v103 offset:18432
	ds_read_b128 v[128:131], v103 offset:20480
	ds_read_b128 v[136:139], v103 offset:22528
	s_waitcnt lgkmcnt(0)
	v_mfma_f32_16x16x32_bf16 v[140:143], v[114:117], v[110:113], v[4:7]
	s_cselect_b64 s[44:45], -1, 0
	s_and_b64 vcc, exec, s[44:45]
	v_mfma_f32_16x16x32_bf16 v[144:147], v[114:117], v[118:121], v[0:3]
	s_nop 2
	ds_read_b128 v[0:3], v64 offset:4096
	ds_read_b128 v[4:7], v64 offset:6144
	v_mfma_f32_16x16x32_bf16 v[148:151], v[114:117], v[128:131], v[16:19]
	s_nop 2
	ds_read_b128 v[16:19], v104
	v_mfma_f32_16x16x32_bf16 v[48:51], v[106:109], v[110:113], v[48:51]
	v_mfma_f32_16x16x32_bf16 v[36:39], v[106:109], v[118:121], v[36:39]
	v_mfma_f32_16x16x32_bf16 v[12:15], v[106:109], v[128:131], v[12:15]
	v_mfma_f32_16x16x32_bf16 v[106:109], v[106:109], v[136:139], v[8:11]
	v_mfma_f32_16x16x32_bf16 v[114:117], v[114:117], v[136:139], v[24:27]
	s_waitcnt lgkmcnt(0)
	v_mfma_f32_16x16x32_bf16 v[156:159], v[0:3], v[118:121], v[28:31]
	v_mfma_f32_16x16x32_bf16 v[160:163], v[0:3], v[128:131], v[32:35]
	v_mfma_f32_16x16x32_bf16 v[44:47], v[0:3], v[136:139], v[44:47]
	v_mfma_f32_16x16x32_bf16 v[52:55], v[4:7], v[118:121], v[52:55]
	v_mfma_f32_16x16x32_bf16 v[56:59], v[4:7], v[128:131], v[56:59]
	ds_read_b128 v[118:121], v105 offset:16384
	ds_read_b128 v[28:31], v104 offset:2048
	ds_read_b128 v[128:131], v105 offset:18432
	v_mfma_f32_16x16x32_bf16 v[60:63], v[4:7], v[136:139], v[60:63]
	ds_read_b128 v[136:139], v105 offset:20480
	ds_read_b128 v[166:169], v105 offset:22528
	v_mfma_f32_16x16x32_bf16 v[152:155], v[0:3], v[110:113], v[20:23]
	s_waitcnt lgkmcnt(0)
	v_mfma_f32_16x16x32_bf16 v[0:3], v[16:19], v[118:121], v[48:51]
	v_mfma_f32_16x16x32_bf16 v[8:11], v[16:19], v[136:139], v[12:15]
	v_mfma_f32_16x16x32_bf16 v[12:15], v[16:19], v[166:169], v[106:109]
	s_nop 0
	ds_read_b128 v[48:51], v104 offset:4096
	s_nop 0
	ds_read_b128 v[106:109], v104 offset:6144
	s_waitcnt vmcnt(0) lgkmcnt(0)
	s_barrier
	s_cbranch_vccnz .Lge4_last0
	s_setprio 1
	v_mfma_f32_16x16x32_bf16 v[110:113], v[4:7], v[110:113], v[40:43]
	s_mov_b32 m0, s59
	v_lshl_add_u64 v[246:247], s[34:35], 0, v[66:67]
	v_lshl_add_u64 v[246:247], v[246:247], 0, s[18:19]
	global_load_lds_dwordx4 v[246:247], off
	v_mfma_f32_16x16x32_bf16 v[4:7], v[16:19], v[128:131], v[36:39]
	s_mov_b32 m0, s60
	v_lshl_add_u64 v[246:247], s[34:35], 0, v[74:75]
	v_lshl_add_u64 v[246:247], v[246:247], 0, s[26:27]
	global_load_lds_dwordx4 v[246:247], off
	v_mfma_f32_16x16x32_bf16 v[16:19], v[28:31], v[118:121], v[140:143]
	s_mov_b32 m0, s61
	v_lshl_add_u64 v[246:247], s[34:35], 0, v[68:69]
	v_lshl_add_u64 v[246:247], v[246:247], 0, s[18:19]
	global_load_lds_dwordx4 v[246:247], off
	v_mfma_f32_16x16x32_bf16 v[20:23], v[28:31], v[128:131], v[144:147]
	s_mov_b32 m0, s62
	v_lshl_add_u64 v[246:247], s[34:35], 0, v[76:77]
	v_lshl_add_u64 v[246:247], v[246:247], 0, s[26:27]
	global_load_lds_dwordx4 v[246:247], off
	v_mfma_f32_16x16x32_bf16 v[24:27], v[28:31], v[136:139], v[148:151]
	s_mov_b32 m0, s63
	v_lshl_add_u64 v[246:247], s[34:35], 0, v[70:71]
	v_lshl_add_u64 v[246:247], v[246:247], 0, s[18:19]
	global_load_lds_dwordx4 v[246:247], off
	v_mfma_f32_16x16x32_bf16 v[28:31], v[28:31], v[166:169], v[114:117]
	s_mov_b32 m0, s64
	v_lshl_add_u64 v[246:247], s[34:35], 0, v[78:79]
	v_lshl_add_u64 v[246:247], v[246:247], 0, s[26:27]
	global_load_lds_dwordx4 v[246:247], off
	s_waitcnt lgkmcnt(0)
	v_mfma_f32_16x16x32_bf16 v[32:35], v[48:51], v[118:121], v[152:155]
	s_mov_b32 m0, s65
	v_lshl_add_u64 v[246:247], s[34:35], 0, v[72:73]
	v_lshl_add_u64 v[246:247], v[246:247], 0, s[18:19]
	global_load_lds_dwordx4 v[246:247], off
	v_mfma_f32_16x16x32_bf16 v[36:39], v[48:51], v[128:131], v[156:159]
	s_mov_b32 m0, s68
	v_lshl_add_u64 v[246:247], s[34:35], 0, v[80:81]
	v_lshl_add_u64 v[246:247], v[246:247], 0, s[26:27]
	global_load_lds_dwordx4 v[246:247], off
	v_mfma_f32_16x16x32_bf16 v[40:43], v[48:51], v[136:139], v[160:163]
	v_mfma_f32_16x16x32_bf16 v[44:47], v[48:51], v[166:169], v[44:47]
	v_mfma_f32_16x16x32_bf16 v[48:51], v[106:109], v[118:121], v[110:113]
	v_mfma_f32_16x16x32_bf16 v[52:55], v[106:109], v[128:131], v[52:55]
	v_mfma_f32_16x16x32_bf16 v[56:59], v[106:109], v[136:139], v[56:59]
	v_mfma_f32_16x16x32_bf16 v[60:63], v[106:109], v[166:169], v[60:63]
	s_setprio 0
	s_branch .LBB0_959

; #define GBAR() do { asm volatile("s_waitcnt vmcnt(0) lgkmcnt(0)" ::: "memory"); __builtin_amdgcn_s_barrier(); } while (0)
; template <int EPI, bool GUARD>
; DEVI void gemm_tile(const Params& p, const bf16_t* __restrict__ A, int lda, const bf16_t* __restrict__ Bt, int ldb, int K,
;                           int row_base, int row_lo, int row_hi, int tile_n, int layer, int which, char* lds) {
;     ...
;   const int swz = c16 >> 1;
;   int koff[2];
; #pragma unroll
;   for (int ks = 0; ks < 2; ++ks) koff[ks] = ((ks * 4 + q4) ^ swz) << 4;
;   const int arow = (wr * 64 + c16) * 128, brow = 16384 + (wc * 64 + c16) * 128;
;     ...
;   GISSUE(0, 0); GBAR();
;   for (int k0 = 0; k0 < K; k0 += 128) {
;     GISSUE(k0 + 64, 1);
;     KSTEPS(0);
;     GBAR();
;     if (k0 + 128 < K) GISSUE(k0 + 128, 0);
;     KSTEPS(1);
;     GBAR();
;   }
.LBB0_1131:
	ds_read_b128 v[82:85], v64 offset:32768
	ds_read_b128 v[86:89], v107 offset:49152
	ds_read_b128 v[90:93], v64 offset:34816
	ds_read_b128 v[94:97], v107 offset:51200
	ds_read_b128 v[110:113], v107 offset:53248
	ds_read_b128 v[114:117], v107 offset:55296
	s_addk_i32 s52, 0x80
	s_waitcnt lgkmcnt(0)
	v_mfma_f32_16x16x32_bf16 v[0:3], v[82:85], v[86:89], v[0:3]
	s_add_u32 s18, s18, 0x100
	s_addc_u32 s19, s19, 0
	s_andn2_b64 vcc, exec, s[26:27]
	v_mfma_f32_16x16x32_bf16 v[4:7], v[82:85], v[94:97], v[4:7]
	v_mfma_f32_16x16x32_bf16 v[8:11], v[82:85], v[110:113], v[8:11]
	v_mfma_f32_16x16x32_bf16 v[12:15], v[82:85], v[114:117], v[12:15]
	v_mfma_f32_16x16x32_bf16 v[16:19], v[90:93], v[86:89], v[16:19]
	v_mfma_f32_16x16x32_bf16 v[20:23], v[90:93], v[94:97], v[20:23]
	v_mfma_f32_16x16x32_bf16 v[24:27], v[90:93], v[110:113], v[24:27]
	v_mfma_f32_16x16x32_bf16 v[28:31], v[90:93], v[114:117], v[28:31]
	ds_read_b128 v[82:85], v64 offset:36864
	ds_read_b128 v[90:93], v64 offset:38912
	s_waitcnt lgkmcnt(0)
	v_mfma_f32_16x16x32_bf16 v[118:121], v[82:85], v[86:89], v[32:35]
	s_nop 2
	ds_read_b128 v[32:35], v108 offset:32768
	v_mfma_f32_16x16x32_bf16 v[122:125], v[82:85], v[94:97], v[36:39]
	v_mfma_f32_16x16x32_bf16 v[126:129], v[82:85], v[110:113], v[40:43]
	v_mfma_f32_16x16x32_bf16 v[82:85], v[82:85], v[114:117], v[44:47]
	v_mfma_f32_16x16x32_bf16 v[86:89], v[90:93], v[86:89], v[48:51]
	v_mfma_f32_16x16x32_bf16 v[94:97], v[90:93], v[94:97], v[52:55]
	v_mfma_f32_16x16x32_bf16 v[110:113], v[90:93], v[110:113], v[56:59]
	v_mfma_f32_16x16x32_bf16 v[90:93], v[90:93], v[114:117], v[60:63]
	ds_read_b128 v[114:117], v109 offset:49152
	ds_read_b128 v[130:133], v108 offset:34816
	ds_read_b128 v[134:137], v109 offset:51200
	ds_read_b128 v[138:141], v109 offset:53248
	ds_read_b128 v[142:145], v109 offset:55296
	s_waitcnt lgkmcnt(0)
	v_mfma_f32_16x16x32_bf16 v[60:63], v[32:35], v[114:117], v[0:3]
	v_mfma_f32_16x16x32_bf16 v[52:55], v[32:35], v[138:141], v[8:11]
	s_nop 1
	ds_read_b128 v[0:3], v108 offset:36864
	ds_read_b128 v[8:11], v108 offset:38912
	s_waitcnt vmcnt(0) lgkmcnt(0)
	s_barrier
	s_cbranch_vccz .Lge5_exit1
	s_setprio 1
	v_mfma_f32_16x16x32_bf16 v[56:59], v[32:35], v[134:137], v[4:7]
	s_mov_b32 m0, s53
	v_lshl_add_u64 v[246:247], s[18:19], 0, v[66:67]
	v_lshl_add_u64 v[246:247], v[246:247], 0, s[2:3]
	global_load_lds_dwordx4 v[246:247], off
	v_mfma_f32_16x16x32_bf16 v[48:51], v[32:35], v[142:145], v[12:15]
	s_mov_b32 m0, s57
	v_lshl_add_u64 v[246:247], s[18:19], 0, v[74:75]
	v_lshl_add_u64 v[246:247], v[246:247], 0, s[4:5]
	global_load_lds_dwordx4 v[246:247], off
	v_mfma_f32_16x16x32_bf16 v[44:47], v[130:133], v[114:117], v[16:19]
	s_mov_b32 m0, s54
	v_lshl_add_u64 v[246:247], s[18:19], 0, v[68:69]
	v_lshl_add_u64 v[246:247], v[246:247], 0, s[2:3]
	global_load_lds_dwordx4 v[246:247], off
	v_mfma_f32_16x16x32_bf16 v[40:43], v[130:133], v[134:137], v[20:23]
	s_mov_b32 m0, s55
	v_lshl_add_u64 v[246:247], s[18:19], 0, v[76:77]
	v_lshl_add_u64 v[246:247], v[246:247], 0, s[4:5]
	global_load_lds_dwordx4 v[246:247], off
	v_mfma_f32_16x16x32_bf16 v[36:39], v[130:133], v[138:141], v[24:27]
	s_mov_b32 m0, s58
	v_lshl_add_u64 v[246:247], s[18:19], 0, v[70:71]
	v_lshl_add_u64 v[246:247], v[246:247], 0, s[2:3]
	global_load_lds_dwordx4 v[246:247], off
	v_mfma_f32_16x16x32_bf16 v[32:35], v[130:133], v[142:145], v[28:31]
	s_mov_b32 m0, s56
	v_lshl_add_u64 v[246:247], s[18:19], 0, v[78:79]
	v_lshl_add_u64 v[246:247], v[246:247], 0, s[4:5]
	global_load_lds_dwordx4 v[246:247], off
	s_waitcnt lgkmcnt(0)
	v_mfma_f32_16x16x32_bf16 v[28:31], v[0:3], v[114:117], v[118:121]
	s_mov_b32 m0, s59
	v_lshl_add_u64 v[246:247], s[18:19], 0, v[72:73]
	v_lshl_add_u64 v[246:247], v[246:247], 0, s[2:3]
	global_load_lds_dwordx4 v[246:247], off
	v_mfma_f32_16x16x32_bf16 v[24:27], v[0:3], v[134:137], v[122:125]
	s_mov_b32 m0, s60
	v_lshl_add_u64 v[246:247], s[18:19], 0, v[80:81]
	v_lshl_add_u64 v[246:247], v[246:247], 0, s[4:5]
	global_load_lds_dwordx4 v[246:247], off
	v_mfma_f32_16x16x32_bf16 v[16:19], v[0:3], v[138:141], v[126:129]
	v_mfma_f32_16x16x32_bf16 v[12:15], v[0:3], v[142:145], v[82:85]
	v_mfma_f32_16x16x32_bf16 v[4:7], v[8:11], v[114:117], v[86:89]
	v_mfma_f32_16x16x32_bf16 v[0:3], v[8:11], v[134:137], v[94:97]
	v_mfma_f32_16x16x32_bf16 v[20:23], v[8:11], v[138:141], v[110:113]
	v_mfma_f32_16x16x32_bf16 v[8:11], v[8:11], v[142:145], v[90:93]
	s_cmpk_gt_u32 s52, 0x37f
	s_cselect_b64 s[26:27], -1, 0
	s_and_b64 vcc, exec, s[26:27]
	s_setprio 0
	s_branch .Lge5_k0

; #define GBAR() do { asm volatile("s_waitcnt vmcnt(0) lgkmcnt(0)" ::: "memory"); __builtin_amdgcn_s_barrier(); } while (0)
; template <int EPI, bool GUARD>
; DEVI void gemm_tile(const Params& p, const bf16_t* __restrict__ A, int lda, const bf16_t* __restrict__ Bt, int ldb, int K,
;                           int row_base, int row_lo, int row_hi, int tile_n, int layer, int which, char* lds) {
;     ...
;   const int swz = c16 >> 1;
;   int koff[2];
; #pragma unroll
;   for (int ks = 0; ks < 2; ++ks) koff[ks] = ((ks * 4 + q4) ^ swz) << 4;
;   const int arow = (wr * 64 + c16) * 128, brow = 16384 + (wc * 64 + c16) * 128;
;     ...
;   GISSUE(0, 0); GBAR();
;   for (int k0 = 0; k0 < K; k0 += 128) {
;     GISSUE(k0 + 64, 1);
;     KSTEPS(0);
;     GBAR();
;     if (k0 + 128 < K) GISSUE(k0 + 128, 0);
;     KSTEPS(1);
;     GBAR();
;   }
.Lge5_k0:
	ds_read_b128 v[110:113], v64
	ds_read_b128 v[114:117], v107 offset:16384
	ds_read_b128 v[118:121], v64 offset:2048
	ds_read_b128 v[122:125], v107 offset:18432
	ds_read_b128 v[126:129], v107 offset:20480
	ds_read_b128 v[130:133], v107 offset:22528
	s_waitcnt lgkmcnt(0)
	v_mfma_f32_16x16x32_bf16 v[60:63], v[110:113], v[114:117], v[60:63]
	v_mfma_f32_16x16x32_bf16 v[56:59], v[110:113], v[122:125], v[56:59]
	v_mfma_f32_16x16x32_bf16 v[52:55], v[110:113], v[126:129], v[52:55]
	v_mfma_f32_16x16x32_bf16 v[48:51], v[110:113], v[130:133], v[48:51]
	v_mfma_f32_16x16x32_bf16 v[44:47], v[118:121], v[114:117], v[44:47]
	v_mfma_f32_16x16x32_bf16 v[40:43], v[118:121], v[122:125], v[40:43]
	v_mfma_f32_16x16x32_bf16 v[36:39], v[118:121], v[126:129], v[36:39]
	v_mfma_f32_16x16x32_bf16 v[32:35], v[118:121], v[130:133], v[32:35]
	ds_read_b128 v[110:113], v64 offset:4096
	ds_read_b128 v[118:121], v64 offset:6144
	s_waitcnt lgkmcnt(0)
	v_mfma_f32_16x16x32_bf16 v[134:137], v[110:113], v[114:117], v[28:31]
	v_mfma_f32_16x16x32_bf16 v[138:141], v[110:113], v[122:125], v[24:27]
	v_mfma_f32_16x16x32_bf16 v[142:145], v[110:113], v[126:129], v[16:19]
	v_mfma_f32_16x16x32_bf16 v[110:113], v[110:113], v[130:133], v[12:15]
	s_nop 2
	ds_read_b128 v[12:15], v108
	v_mfma_f32_16x16x32_bf16 v[114:117], v[118:121], v[114:117], v[4:7]
	v_mfma_f32_16x16x32_bf16 v[122:125], v[118:121], v[122:125], v[0:3]
	v_mfma_f32_16x16x32_bf16 v[126:129], v[118:121], v[126:129], v[20:23]
	v_mfma_f32_16x16x32_bf16 v[118:121], v[118:121], v[130:133], v[8:11]
	ds_read_b128 v[130:133], v109 offset:16384
	ds_read_b128 v[28:31], v108 offset:2048
	ds_read_b128 v[146:149], v109 offset:18432
	s_waitcnt lgkmcnt(0)
	v_mfma_f32_16x16x32_bf16 v[0:3], v[12:15], v[130:133], v[60:63]
	v_mfma_f32_16x16x32_bf16 v[4:7], v[12:15], v[146:149], v[56:59]
	s_nop 2
	ds_read_b128 v[56:59], v109 offset:20480
	ds_read_b128 v[60:63], v109 offset:22528
	v_mfma_f32_16x16x32_bf16 v[16:19], v[28:31], v[130:133], v[44:47]
	s_nop 2
	ds_read_b128 v[44:47], v108 offset:4096
	ds_read_b128 v[150:153], v108 offset:6144
	s_waitcnt vmcnt(0) lgkmcnt(0)
	s_barrier
	s_cbranch_vccnz .Lge5_last0
	s_setprio 1
	s_waitcnt lgkmcnt(0)
	v_mfma_f32_16x16x32_bf16 v[8:11], v[12:15], v[56:59], v[52:55]
	s_mov_b32 m0, s40
	v_lshl_add_u64 v[246:247], s[18:19], 0, v[66:67]
	v_lshl_add_u64 v[246:247], v[246:247], 0, s[6:7]
	global_load_lds_dwordx4 v[246:247], off
	v_mfma_f32_16x16x32_bf16 v[12:15], v[12:15], v[60:63], v[48:51]
	s_mov_b32 m0, s41
	v_lshl_add_u64 v[246:247], s[18:19], 0, v[74:75]
	v_lshl_add_u64 v[246:247], v[246:247], 0, s[8:9]
	global_load_lds_dwordx4 v[246:247], off
	v_mfma_f32_16x16x32_bf16 v[20:23], v[28:31], v[146:149], v[40:43]
	s_mov_b32 m0, s42
	v_lshl_add_u64 v[246:247], s[18:19], 0, v[68:69]
	v_lshl_add_u64 v[246:247], v[246:247], 0, s[6:7]
	global_load_lds_dwordx4 v[246:247], off
	v_mfma_f32_16x16x32_bf16 v[24:27], v[28:31], v[56:59], v[36:39]
	s_mov_b32 m0, s43
	v_lshl_add_u64 v[246:247], s[18:19], 0, v[76:77]
	v_lshl_add_u64 v[246:247], v[246:247], 0, s[8:9]
	global_load_lds_dwordx4 v[246:247], off
	v_mfma_f32_16x16x32_bf16 v[28:31], v[28:31], v[60:63], v[32:35]
	s_mov_b32 m0, s44
	v_lshl_add_u64 v[246:247], s[18:19], 0, v[70:71]
	v_lshl_add_u64 v[246:247], v[246:247], 0, s[6:7]
	global_load_lds_dwordx4 v[246:247], off
	v_mfma_f32_16x16x32_bf16 v[32:35], v[44:47], v[130:133], v[134:137]
	s_mov_b32 m0, s45
	v_lshl_add_u64 v[246:247], s[18:19], 0, v[78:79]
	v_lshl_add_u64 v[246:247], v[246:247], 0, s[8:9]
	global_load_lds_dwordx4 v[246:247], off
	v_mfma_f32_16x16x32_bf16 v[36:39], v[44:47], v[146:149], v[138:141]
	s_mov_b32 m0, s46
	v_lshl_add_u64 v[246:247], s[18:19], 0, v[72:73]
	v_lshl_add_u64 v[246:247], v[246:247], 0, s[6:7]
	global_load_lds_dwordx4 v[246:247], off
	v_mfma_f32_16x16x32_bf16 v[40:43], v[44:47], v[56:59], v[142:145]
	s_mov_b32 m0, s47
	v_lshl_add_u64 v[246:247], s[18:19], 0, v[80:81]
	v_lshl_add_u64 v[246:247], v[246:247], 0, s[8:9]
	global_load_lds_dwordx4 v[246:247], off
	v_mfma_f32_16x16x32_bf16 v[44:47], v[44:47], v[60:63], v[110:113]
	v_mfma_f32_16x16x32_bf16 v[48:51], v[150:153], v[130:133], v[114:117]
	v_mfma_f32_16x16x32_bf16 v[52:55], v[150:153], v[146:149], v[122:125]
	v_mfma_f32_16x16x32_bf16 v[56:59], v[150:153], v[56:59], v[126:129]
	v_mfma_f32_16x16x32_bf16 v[60:63], v[150:153], v[60:63], v[118:121]
	s_setprio 0
	s_branch .LBB0_1131

; #define GBAR() do { asm volatile("s_waitcnt vmcnt(0) lgkmcnt(0)" ::: "memory"); __builtin_amdgcn_s_barrier(); } while (0)
; template <int EPI, bool GUARD>
; DEVI void gemm_tile(const Params& p, const bf16_t* __restrict__ A, int lda, const bf16_t* __restrict__ Bt, int ldb, int K,
;                           int row_base, int row_lo, int row_hi, int tile_n, int layer, int which, char* lds) {
;     ...
;   const int swz = c16 >> 1;
;   int koff[2];
; #pragma unroll
;   for (int ks = 0; ks < 2; ++ks) koff[ks] = ((ks * 4 + q4) ^ swz) << 4;
;   const int arow = (wr * 64 + c16) * 128, brow = 16384 + (wc * 64 + c16) * 128;
;     ...
;   GISSUE(0, 0); GBAR();
;   for (int k0 = 0; k0 < K; k0 += 128) {
;     GISSUE(k0 + 64, 1);
;     KSTEPS(0);
;     GBAR();
;     if (k0 + 128 < K) GISSUE(k0 + 128, 0);
;     KSTEPS(1);
;     GBAR();
;   }
.LBB0_1258:
	ds_read_b128 v[82:85], v64 offset:32768
	ds_read_b128 v[86:89], v112 offset:49152
	ds_read_b128 v[90:93], v64 offset:34816
	ds_read_b128 v[94:97], v112 offset:51200
	ds_read_b128 v[116:119], v112 offset:53248
	ds_read_b128 v[120:123], v112 offset:55296
	s_addk_i32 s51, 0x80
	s_waitcnt lgkmcnt(0)
	v_mfma_f32_16x16x32_bf16 v[0:3], v[82:85], v[86:89], v[0:3]
	s_add_u32 s2, s2, 0x100
	s_addc_u32 s3, s3, 0
	s_and_b64 vcc, exec, s[4:5]
	v_mfma_f32_16x16x32_bf16 v[4:7], v[82:85], v[94:97], v[4:7]
	v_mfma_f32_16x16x32_bf16 v[8:11], v[82:85], v[116:119], v[8:11]
	v_mfma_f32_16x16x32_bf16 v[12:15], v[82:85], v[120:123], v[12:15]
	v_mfma_f32_16x16x32_bf16 v[82:85], v[90:93], v[86:89], v[16:19]
	v_mfma_f32_16x16x32_bf16 v[20:23], v[90:93], v[94:97], v[20:23]
	v_mfma_f32_16x16x32_bf16 v[24:27], v[90:93], v[116:119], v[24:27]
	v_mfma_f32_16x16x32_bf16 v[28:31], v[90:93], v[120:123], v[28:31]
	ds_read_b128 v[16:19], v64 offset:36864
	ds_read_b128 v[90:93], v64 offset:38912
	s_waitcnt lgkmcnt(0)
	v_mfma_f32_16x16x32_bf16 v[124:127], v[16:19], v[86:89], v[32:35]
	v_mfma_f32_16x16x32_bf16 v[36:39], v[16:19], v[94:97], v[36:39]
	v_mfma_f32_16x16x32_bf16 v[40:43], v[16:19], v[116:119], v[40:43]
	v_mfma_f32_16x16x32_bf16 v[44:47], v[16:19], v[120:123], v[44:47]
	ds_read_b128 v[16:19], v113 offset:32768
	v_mfma_f32_16x16x32_bf16 v[86:89], v[90:93], v[86:89], v[48:51]
	v_mfma_f32_16x16x32_bf16 v[52:55], v[90:93], v[94:97], v[52:55]
	v_mfma_f32_16x16x32_bf16 v[56:59], v[90:93], v[116:119], v[56:59]
	v_mfma_f32_16x16x32_bf16 v[60:63], v[90:93], v[120:123], v[60:63]
	ds_read_b128 v[90:93], v114 offset:49152
	ds_read_b128 v[32:35], v113 offset:34816
	ds_read_b128 v[94:97], v114 offset:51200
	ds_read_b128 v[116:119], v114 offset:53248
	ds_read_b128 v[120:123], v114 offset:55296
	s_waitcnt lgkmcnt(0)
	v_mfma_f32_16x16x32_bf16 v[0:3], v[16:19], v[90:93], v[0:3]
	v_mfma_f32_16x16x32_bf16 v[4:7], v[16:19], v[94:97], v[4:7]
	v_mfma_f32_16x16x32_bf16 v[8:11], v[16:19], v[116:119], v[8:11]
	v_mfma_f32_16x16x32_bf16 v[16:19], v[16:19], v[120:123], v[12:15]
	v_mfma_f32_16x16x32_bf16 v[12:15], v[32:35], v[90:93], v[82:85]
	ds_read_b128 v[48:51], v113 offset:36864
	s_nop 1
	ds_read_b128 v[82:85], v113 offset:38912
	s_waitcnt vmcnt(0) lgkmcnt(0)
	s_barrier
	s_cbranch_vccnz .Lge6_exit1
	s_setprio 1
	v_mfma_f32_16x16x32_bf16 v[20:23], v[32:35], v[94:97], v[20:23]
	s_add_i32 m0, s52, 0x8000
	v_lshl_add_u64 v[246:247], s[2:3], 0, v[66:67]
	v_lshl_add_u64 v[246:247], v[246:247], 0, s[18:19]
	global_load_lds_dwordx4 v[246:247], off
	v_mfma_f32_16x16x32_bf16 v[24:27], v[32:35], v[116:119], v[24:27]
	s_add_i32 m0, s52, 0xc000
	v_lshl_add_u64 v[246:247], s[2:3], 0, v[74:75]
	v_lshl_add_u64 v[246:247], v[246:247], 0, s[26:27]
	global_load_lds_dwordx4 v[246:247], off
	v_mfma_f32_16x16x32_bf16 v[32:35], v[32:35], v[120:123], v[28:31]
	s_add_i32 m0, s52, 0x8400
	v_lshl_add_u64 v[246:247], s[2:3], 0, v[68:69]
	v_lshl_add_u64 v[246:247], v[246:247], 0, s[18:19]
	global_load_lds_dwordx4 v[246:247], off
	s_waitcnt lgkmcnt(0)
	v_mfma_f32_16x16x32_bf16 v[28:31], v[48:51], v[90:93], v[124:127]
	s_add_i32 m0, s52, 0xc400
	v_lshl_add_u64 v[246:247], s[2:3], 0, v[76:77]
	v_lshl_add_u64 v[246:247], v[246:247], 0, s[26:27]
	global_load_lds_dwordx4 v[246:247], off
	v_mfma_f32_16x16x32_bf16 v[36:39], v[48:51], v[94:97], v[36:39]
	s_add_i32 m0, s52, 0x8800
	v_lshl_add_u64 v[246:247], s[2:3], 0, v[70:71]
	v_lshl_add_u64 v[246:247], v[246:247], 0, s[18:19]
	global_load_lds_dwordx4 v[246:247], off
	v_mfma_f32_16x16x32_bf16 v[40:43], v[48:51], v[116:119], v[40:43]
	s_add_i32 m0, s52, 0xc800
	v_lshl_add_u64 v[246:247], s[2:3], 0, v[78:79]
	v_lshl_add_u64 v[246:247], v[246:247], 0, s[26:27]
	global_load_lds_dwordx4 v[246:247], off
	v_mfma_f32_16x16x32_bf16 v[48:51], v[48:51], v[120:123], v[44:47]
	s_add_i32 m0, s58, 0x8000
	v_lshl_add_u64 v[246:247], s[2:3], 0, v[72:73]
	v_lshl_add_u64 v[246:247], v[246:247], 0, s[18:19]
	global_load_lds_dwordx4 v[246:247], off
	v_mfma_f32_16x16x32_bf16 v[44:47], v[82:85], v[90:93], v[86:89]
	s_add_i32 m0, s58, 0xc000
	v_lshl_add_u64 v[246:247], s[2:3], 0, v[80:81]
	v_lshl_add_u64 v[246:247], v[246:247], 0, s[26:27]
	global_load_lds_dwordx4 v[246:247], off
	v_mfma_f32_16x16x32_bf16 v[52:55], v[82:85], v[94:97], v[52:55]
	v_mfma_f32_16x16x32_bf16 v[56:59], v[82:85], v[116:119], v[56:59]
	v_mfma_f32_16x16x32_bf16 v[60:63], v[82:85], v[120:123], v[60:63]
	s_cmpk_gt_u32 s51, 0x37f
	s_setprio 0
	s_branch .Lge6_k0

; #define GBAR() do { asm volatile("s_waitcnt vmcnt(0) lgkmcnt(0)" ::: "memory"); __builtin_amdgcn_s_barrier(); } while (0)
; template <int EPI, bool GUARD>
; DEVI void gemm_tile(const Params& p, const bf16_t* __restrict__ A, int lda, const bf16_t* __restrict__ Bt, int ldb, int K,
;                           int row_base, int row_lo, int row_hi, int tile_n, int layer, int which, char* lds) {
;     ...
;   const int swz = c16 >> 1;
;   int koff[2];
; #pragma unroll
;   for (int ks = 0; ks < 2; ++ks) koff[ks] = ((ks * 4 + q4) ^ swz) << 4;
;   const int arow = (wr * 64 + c16) * 128, brow = 16384 + (wc * 64 + c16) * 128;
;     ...
;   GISSUE(0, 0); GBAR();
;   for (int k0 = 0; k0 < K; k0 += 128) {
;     GISSUE(k0 + 64, 1);
;     KSTEPS(0);
;     GBAR();
;     if (k0 + 128 < K) GISSUE(k0 + 128, 0);
;     KSTEPS(1);
;     GBAR();
;   }
.Lge6_k0:
	ds_read_b128 v[116:119], v64
	ds_read_b128 v[120:123], v112 offset:16384
	ds_read_b128 v[124:127], v64 offset:2048
	ds_read_b128 v[128:131], v112 offset:18432
	ds_read_b128 v[132:135], v112 offset:20480
	ds_read_b128 v[136:139], v112 offset:22528
	s_waitcnt lgkmcnt(0)
	v_mfma_f32_16x16x32_bf16 v[0:3], v[116:119], v[120:123], v[0:3]
	s_cselect_b64 s[4:5], -1, 0
	s_and_b64 vcc, exec, s[4:5]
	v_mfma_f32_16x16x32_bf16 v[4:7], v[116:119], v[128:131], v[4:7]
	v_mfma_f32_16x16x32_bf16 v[8:11], v[116:119], v[132:135], v[8:11]
	v_mfma_f32_16x16x32_bf16 v[16:19], v[116:119], v[136:139], v[16:19]
	v_mfma_f32_16x16x32_bf16 v[116:119], v[124:127], v[120:123], v[12:15]
	v_mfma_f32_16x16x32_bf16 v[20:23], v[124:127], v[128:131], v[20:23]
	v_mfma_f32_16x16x32_bf16 v[24:27], v[124:127], v[132:135], v[24:27]
	v_mfma_f32_16x16x32_bf16 v[32:35], v[124:127], v[136:139], v[32:35]
	ds_read_b128 v[12:15], v64 offset:4096
	ds_read_b128 v[124:127], v64 offset:6144
	s_waitcnt lgkmcnt(0)
	v_mfma_f32_16x16x32_bf16 v[140:143], v[12:15], v[120:123], v[28:31]
	v_mfma_f32_16x16x32_bf16 v[36:39], v[12:15], v[128:131], v[36:39]
	v_mfma_f32_16x16x32_bf16 v[40:43], v[12:15], v[132:135], v[40:43]
	v_mfma_f32_16x16x32_bf16 v[48:51], v[12:15], v[136:139], v[48:51]
	ds_read_b128 v[12:15], v113
	v_mfma_f32_16x16x32_bf16 v[120:123], v[124:127], v[120:123], v[44:47]
	v_mfma_f32_16x16x32_bf16 v[52:55], v[124:127], v[128:131], v[52:55]
	v_mfma_f32_16x16x32_bf16 v[56:59], v[124:127], v[132:135], v[56:59]
	v_mfma_f32_16x16x32_bf16 v[60:63], v[124:127], v[136:139], v[60:63]
	ds_read_b128 v[124:127], v114 offset:16384
	ds_read_b128 v[28:31], v113 offset:2048
	ds_read_b128 v[128:131], v114 offset:18432
	ds_read_b128 v[132:135], v114 offset:20480
	ds_read_b128 v[136:139], v114 offset:22528
	s_waitcnt lgkmcnt(0)
	v_mfma_f32_16x16x32_bf16 v[0:3], v[12:15], v[124:127], v[0:3]
	v_mfma_f32_16x16x32_bf16 v[4:7], v[12:15], v[128:131], v[4:7]
	v_mfma_f32_16x16x32_bf16 v[8:11], v[12:15], v[132:135], v[8:11]
	v_mfma_f32_16x16x32_bf16 v[12:15], v[12:15], v[136:139], v[16:19]
	v_mfma_f32_16x16x32_bf16 v[16:19], v[28:31], v[124:127], v[116:119]
	ds_read_b128 v[44:47], v113 offset:4096
	s_nop 1
	ds_read_b128 v[116:119], v113 offset:6144
	s_waitcnt vmcnt(0) lgkmcnt(0)
	s_barrier
	s_cbranch_vccnz .Lge6_last0
	s_setprio 1
	v_mfma_f32_16x16x32_bf16 v[20:23], v[28:31], v[128:131], v[20:23]
	s_mov_b32 m0, s52
	v_lshl_add_u64 v[246:247], s[2:3], 0, v[66:67]
	v_lshl_add_u64 v[246:247], v[246:247], 0, s[28:29]
	global_load_lds_dwordx4 v[246:247], off
	v_mfma_f32_16x16x32_bf16 v[24:27], v[28:31], v[132:135], v[24:27]
	s_mov_b32 m0, s53
	v_lshl_add_u64 v[246:247], s[2:3], 0, v[74:75]
	v_lshl_add_u64 v[246:247], v[246:247], 0, s[30:31]
	global_load_lds_dwordx4 v[246:247], off
	v_mfma_f32_16x16x32_bf16 v[28:31], v[28:31], v[136:139], v[32:35]
	s_mov_b32 m0, s54
	v_lshl_add_u64 v[246:247], s[2:3], 0, v[68:69]
	v_lshl_add_u64 v[246:247], v[246:247], 0, s[28:29]
	global_load_lds_dwordx4 v[246:247], off
	s_waitcnt lgkmcnt(0)
	v_mfma_f32_16x16x32_bf16 v[32:35], v[44:47], v[124:127], v[140:143]
	s_mov_b32 m0, s55
	v_lshl_add_u64 v[246:247], s[2:3], 0, v[76:77]
	v_lshl_add_u64 v[246:247], v[246:247], 0, s[30:31]
	global_load_lds_dwordx4 v[246:247], off
	v_mfma_f32_16x16x32_bf16 v[36:39], v[44:47], v[128:131], v[36:39]
	s_mov_b32 m0, s56
	v_lshl_add_u64 v[246:247], s[2:3], 0, v[70:71]
	v_lshl_add_u64 v[246:247], v[246:247], 0, s[28:29]
	global_load_lds_dwordx4 v[246:247], off
	v_mfma_f32_16x16x32_bf16 v[40:43], v[44:47], v[132:135], v[40:43]
	s_mov_b32 m0, s57
	v_lshl_add_u64 v[246:247], s[2:3], 0, v[78:79]
	v_lshl_add_u64 v[246:247], v[246:247], 0, s[30:31]
	global_load_lds_dwordx4 v[246:247], off
	v_mfma_f32_16x16x32_bf16 v[44:47], v[44:47], v[136:139], v[48:51]
	s_mov_b32 m0, s58
	v_lshl_add_u64 v[246:247], s[2:3], 0, v[72:73]
	v_lshl_add_u64 v[246:247], v[246:247], 0, s[28:29]
	global_load_lds_dwordx4 v[246:247], off
	v_mfma_f32_16x16x32_bf16 v[48:51], v[116:119], v[124:127], v[120:123]
	s_mov_b32 m0, s59
	v_lshl_add_u64 v[246:247], s[2:3], 0, v[80:81]
	v_lshl_add_u64 v[246:247], v[246:247], 0, s[30:31]
	global_load_lds_dwordx4 v[246:247], off
	v_mfma_f32_16x16x32_bf16 v[52:55], v[116:119], v[128:131], v[52:55]
	v_mfma_f32_16x16x32_bf16 v[56:59], v[116:119], v[132:135], v[56:59]
	v_mfma_f32_16x16x32_bf16 v[60:63], v[116:119], v[136:139], v[60:63]
	s_setprio 0
	s_branch .LBB0_1258

; #define GBAR() do { asm volatile("s_waitcnt vmcnt(0) lgkmcnt(0)" ::: "memory"); __builtin_amdgcn_s_barrier(); } while (0)
; template <int EPI, bool GUARD>
; DEVI void gemm_tile(const Params& p, const bf16_t* __restrict__ A, int lda, const bf16_t* __restrict__ Bt, int ldb, int K,
;                           int row_base, int row_lo, int row_hi, int tile_n, int layer, int which, char* lds) {
;     ...
;   const int swz = c16 >> 1;
;   int koff[2];
; #pragma unroll
;   for (int ks = 0; ks < 2; ++ks) koff[ks] = ((ks * 4 + q4) ^ swz) << 4;
;   const int arow = (wr * 64 + c16) * 128, brow = 16384 + (wc * 64 + c16) * 128;
;     ...
;   GISSUE(0, 0); GBAR();
;   for (int k0 = 0; k0 < K; k0 += 128) {
;     GISSUE(k0 + 64, 1);
;     KSTEPS(0);
;     GBAR();
;     if (k0 + 128 < K) GISSUE(k0 + 128, 0);
;     KSTEPS(1);
;     GBAR();
;   }
.LBB0_1336:
	ds_read_b128 v[82:85], v64 offset:32768
	ds_read_b128 v[86:89], v107 offset:49152
	ds_read_b128 v[90:93], v64 offset:34816
	ds_read_b128 v[94:97], v107 offset:51200
	ds_read_b128 v[110:113], v107 offset:53248
	ds_read_b128 v[114:117], v107 offset:55296
	s_addk_i32 s44, 0x80
	s_waitcnt lgkmcnt(0)
	v_mfma_f32_16x16x32_bf16 v[0:3], v[82:85], v[86:89], v[0:3]
	s_add_u32 s18, s18, 0x100
	s_addc_u32 s19, s19, 0
	s_andn2_b64 vcc, exec, s[20:21]
	v_mfma_f32_16x16x32_bf16 v[4:7], v[82:85], v[94:97], v[4:7]
	v_mfma_f32_16x16x32_bf16 v[8:11], v[82:85], v[110:113], v[8:11]
	v_mfma_f32_16x16x32_bf16 v[12:15], v[82:85], v[114:117], v[12:15]
	v_mfma_f32_16x16x32_bf16 v[16:19], v[90:93], v[86:89], v[16:19]
	v_mfma_f32_16x16x32_bf16 v[20:23], v[90:93], v[94:97], v[20:23]
	v_mfma_f32_16x16x32_bf16 v[24:27], v[90:93], v[110:113], v[24:27]
	v_mfma_f32_16x16x32_bf16 v[28:31], v[90:93], v[114:117], v[28:31]
	ds_read_b128 v[82:85], v64 offset:36864
	ds_read_b128 v[90:93], v64 offset:38912
	s_waitcnt lgkmcnt(0)
	v_mfma_f32_16x16x32_bf16 v[118:121], v[82:85], v[86:89], v[32:35]
	s_nop 2
	ds_read_b128 v[32:35], v108 offset:32768
	v_mfma_f32_16x16x32_bf16 v[122:125], v[82:85], v[94:97], v[36:39]
	v_mfma_f32_16x16x32_bf16 v[126:129], v[82:85], v[110:113], v[40:43]
	v_mfma_f32_16x16x32_bf16 v[82:85], v[82:85], v[114:117], v[44:47]
	v_mfma_f32_16x16x32_bf16 v[86:89], v[90:93], v[86:89], v[48:51]
	v_mfma_f32_16x16x32_bf16 v[94:97], v[90:93], v[94:97], v[52:55]
	v_mfma_f32_16x16x32_bf16 v[110:113], v[90:93], v[110:113], v[56:59]
	v_mfma_f32_16x16x32_bf16 v[90:93], v[90:93], v[114:117], v[60:63]
	ds_read_b128 v[114:117], v109 offset:49152
	ds_read_b128 v[130:133], v108 offset:34816
	ds_read_b128 v[134:137], v109 offset:51200
	ds_read_b128 v[138:141], v109 offset:53248
	ds_read_b128 v[142:145], v109 offset:55296
	s_waitcnt lgkmcnt(0)
	v_mfma_f32_16x16x32_bf16 v[60:63], v[32:35], v[114:117], v[0:3]
	v_mfma_f32_16x16x32_bf16 v[52:55], v[32:35], v[138:141], v[8:11]
	s_nop 1
	ds_read_b128 v[0:3], v108 offset:36864
	ds_read_b128 v[8:11], v108 offset:38912
	s_waitcnt vmcnt(0) lgkmcnt(0)
	s_barrier
	s_cbranch_vccz .Lge7_exit1
	s_setprio 1
	v_mfma_f32_16x16x32_bf16 v[56:59], v[32:35], v[134:137], v[4:7]
	s_mov_b32 m0, s45
	v_lshl_add_u64 v[246:247], s[18:19], 0, v[66:67]
	v_lshl_add_u64 v[246:247], v[246:247], 0, s[2:3]
	global_load_lds_dwordx4 v[246:247], off
	v_mfma_f32_16x16x32_bf16 v[48:51], v[32:35], v[142:145], v[12:15]
	s_mov_b32 m0, s50
	v_lshl_add_u64 v[246:247], s[18:19], 0, v[74:75]
	v_lshl_add_u64 v[246:247], v[246:247], 0, s[4:5]
	global_load_lds_dwordx4 v[246:247], off
	v_mfma_f32_16x16x32_bf16 v[44:47], v[130:133], v[114:117], v[16:19]
	s_mov_b32 m0, s46
	v_lshl_add_u64 v[246:247], s[18:19], 0, v[68:69]
	v_lshl_add_u64 v[246:247], v[246:247], 0, s[2:3]
	global_load_lds_dwordx4 v[246:247], off
	v_mfma_f32_16x16x32_bf16 v[40:43], v[130:133], v[134:137], v[20:23]
	s_mov_b32 m0, s47
	v_lshl_add_u64 v[246:247], s[18:19], 0, v[76:77]
	v_lshl_add_u64 v[246:247], v[246:247], 0, s[4:5]
	global_load_lds_dwordx4 v[246:247], off
	v_mfma_f32_16x16x32_bf16 v[36:39], v[130:133], v[138:141], v[24:27]
	s_mov_b32 m0, s48
	v_lshl_add_u64 v[246:247], s[18:19], 0, v[70:71]
	v_lshl_add_u64 v[246:247], v[246:247], 0, s[2:3]
	global_load_lds_dwordx4 v[246:247], off
	v_mfma_f32_16x16x32_bf16 v[32:35], v[130:133], v[142:145], v[28:31]
	s_mov_b32 m0, s49
	v_lshl_add_u64 v[246:247], s[18:19], 0, v[78:79]
	v_lshl_add_u64 v[246:247], v[246:247], 0, s[4:5]
	global_load_lds_dwordx4 v[246:247], off
	s_waitcnt lgkmcnt(0)
	v_mfma_f32_16x16x32_bf16 v[28:31], v[0:3], v[114:117], v[118:121]
	s_mov_b32 m0, s51
	v_lshl_add_u64 v[246:247], s[18:19], 0, v[72:73]
	v_lshl_add_u64 v[246:247], v[246:247], 0, s[2:3]
	global_load_lds_dwordx4 v[246:247], off
	v_mfma_f32_16x16x32_bf16 v[24:27], v[0:3], v[134:137], v[122:125]
	s_mov_b32 m0, s52
	v_lshl_add_u64 v[246:247], s[18:19], 0, v[80:81]
	v_lshl_add_u64 v[246:247], v[246:247], 0, s[4:5]
	global_load_lds_dwordx4 v[246:247], off
	v_mfma_f32_16x16x32_bf16 v[16:19], v[0:3], v[138:141], v[126:129]
	v_mfma_f32_16x16x32_bf16 v[12:15], v[0:3], v[142:145], v[82:85]
	v_mfma_f32_16x16x32_bf16 v[4:7], v[8:11], v[114:117], v[86:89]
	v_mfma_f32_16x16x32_bf16 v[0:3], v[8:11], v[134:137], v[94:97]
	v_mfma_f32_16x16x32_bf16 v[20:23], v[8:11], v[138:141], v[110:113]
	v_mfma_f32_16x16x32_bf16 v[8:11], v[8:11], v[142:145], v[90:93]
	s_cmpk_gt_u32 s44, 0xa7f
	s_cselect_b64 s[20:21], -1, 0
	s_and_b64 vcc, exec, s[20:21]
	s_setprio 0
	s_branch .Lge7_k0

; #define GBAR() do { asm volatile("s_waitcnt vmcnt(0) lgkmcnt(0)" ::: "memory"); __builtin_amdgcn_s_barrier(); } while (0)
; template <int EPI, bool GUARD>
; DEVI void gemm_tile(const Params& p, const bf16_t* __restrict__ A, int lda, const bf16_t* __restrict__ Bt, int ldb, int K,
;                           int row_base, int row_lo, int row_hi, int tile_n, int layer, int which, char* lds) {
;     ...
;   const int swz = c16 >> 1;
;   int koff[2];
; #pragma unroll
;   for (int ks = 0; ks < 2; ++ks) koff[ks] = ((ks * 4 + q4) ^ swz) << 4;
;   const int arow = (wr * 64 + c16) * 128, brow = 16384 + (wc * 64 + c16) * 128;
;     ...
;   GISSUE(0, 0); GBAR();
;   for (int k0 = 0; k0 < K; k0 += 128) {
;     GISSUE(k0 + 64, 1);
;     KSTEPS(0);
;     GBAR();
;     if (k0 + 128 < K) GISSUE(k0 + 128, 0);
;     KSTEPS(1);
;     GBAR();
;   }
.Lge7_k0:
	ds_read_b128 v[110:113], v64
	ds_read_b128 v[114:117], v107 offset:16384
	ds_read_b128 v[118:121], v64 offset:2048
	ds_read_b128 v[122:125], v107 offset:18432
	ds_read_b128 v[126:129], v107 offset:20480
	ds_read_b128 v[130:133], v107 offset:22528
	s_waitcnt lgkmcnt(0)
	v_mfma_f32_16x16x32_bf16 v[60:63], v[110:113], v[114:117], v[60:63]
	v_mfma_f32_16x16x32_bf16 v[56:59], v[110:113], v[122:125], v[56:59]
	v_mfma_f32_16x16x32_bf16 v[52:55], v[110:113], v[126:129], v[52:55]
	v_mfma_f32_16x16x32_bf16 v[48:51], v[110:113], v[130:133], v[48:51]
	v_mfma_f32_16x16x32_bf16 v[44:47], v[118:121], v[114:117], v[44:47]
	v_mfma_f32_16x16x32_bf16 v[40:43], v[118:121], v[122:125], v[40:43]
	v_mfma_f32_16x16x32_bf16 v[36:39], v[118:121], v[126:129], v[36:39]
	v_mfma_f32_16x16x32_bf16 v[32:35], v[118:121], v[130:133], v[32:35]
	ds_read_b128 v[110:113], v64 offset:4096
	ds_read_b128 v[118:121], v64 offset:6144
	s_waitcnt lgkmcnt(0)
	v_mfma_f32_16x16x32_bf16 v[134:137], v[110:113], v[114:117], v[28:31]
	v_mfma_f32_16x16x32_bf16 v[138:141], v[110:113], v[122:125], v[24:27]
	v_mfma_f32_16x16x32_bf16 v[142:145], v[110:113], v[126:129], v[16:19]
	v_mfma_f32_16x16x32_bf16 v[110:113], v[110:113], v[130:133], v[12:15]
	s_nop 2
	ds_read_b128 v[12:15], v108
	v_mfma_f32_16x16x32_bf16 v[114:117], v[118:121], v[114:117], v[4:7]
	v_mfma_f32_16x16x32_bf16 v[122:125], v[118:121], v[122:125], v[0:3]
	v_mfma_f32_16x16x32_bf16 v[126:129], v[118:121], v[126:129], v[20:23]
	v_mfma_f32_16x16x32_bf16 v[118:121], v[118:121], v[130:133], v[8:11]
	ds_read_b128 v[130:133], v109 offset:16384
	ds_read_b128 v[28:31], v108 offset:2048
	ds_read_b128 v[146:149], v109 offset:18432
	s_waitcnt lgkmcnt(0)
	v_mfma_f32_16x16x32_bf16 v[0:3], v[12:15], v[130:133], v[60:63]
	v_mfma_f32_16x16x32_bf16 v[4:7], v[12:15], v[146:149], v[56:59]
	s_nop 2
	ds_read_b128 v[56:59], v109 offset:20480
	ds_read_b128 v[60:63], v109 offset:22528
	v_mfma_f32_16x16x32_bf16 v[16:19], v[28:31], v[130:133], v[44:47]
	s_nop 2
	ds_read_b128 v[44:47], v108 offset:4096
	ds_read_b128 v[150:153], v108 offset:6144
	s_waitcnt vmcnt(0) lgkmcnt(0)
	s_barrier
	s_cbranch_vccnz .Lge7_last0
	s_setprio 1
	s_waitcnt lgkmcnt(0)
	v_mfma_f32_16x16x32_bf16 v[8:11], v[12:15], v[56:59], v[52:55]
	s_mov_b32 m0, s36
	v_lshl_add_u64 v[246:247], s[18:19], 0, v[66:67]
	v_lshl_add_u64 v[246:247], v[246:247], 0, s[6:7]
	global_load_lds_dwordx4 v[246:247], off
	v_mfma_f32_16x16x32_bf16 v[12:15], v[12:15], v[60:63], v[48:51]
	s_mov_b32 m0, s37
	v_lshl_add_u64 v[246:247], s[18:19], 0, v[74:75]
	v_lshl_add_u64 v[246:247], v[246:247], 0, s[8:9]
	global_load_lds_dwordx4 v[246:247], off
	v_mfma_f32_16x16x32_bf16 v[20:23], v[28:31], v[146:149], v[40:43]
	s_mov_b32 m0, s38
	v_lshl_add_u64 v[246:247], s[18:19], 0, v[68:69]
	v_lshl_add_u64 v[246:247], v[246:247], 0, s[6:7]
	global_load_lds_dwordx4 v[246:247], off
	v_mfma_f32_16x16x32_bf16 v[24:27], v[28:31], v[56:59], v[36:39]
	s_mov_b32 m0, s39
	v_lshl_add_u64 v[246:247], s[18:19], 0, v[76:77]
	v_lshl_add_u64 v[246:247], v[246:247], 0, s[8:9]
	global_load_lds_dwordx4 v[246:247], off
	v_mfma_f32_16x16x32_bf16 v[28:31], v[28:31], v[60:63], v[32:35]
	s_mov_b32 m0, s40
	v_lshl_add_u64 v[246:247], s[18:19], 0, v[70:71]
	v_lshl_add_u64 v[246:247], v[246:247], 0, s[6:7]
	global_load_lds_dwordx4 v[246:247], off
	v_mfma_f32_16x16x32_bf16 v[32:35], v[44:47], v[130:133], v[134:137]
	s_mov_b32 m0, s41
	v_lshl_add_u64 v[246:247], s[18:19], 0, v[78:79]
	v_lshl_add_u64 v[246:247], v[246:247], 0, s[8:9]
	global_load_lds_dwordx4 v[246:247], off
	v_mfma_f32_16x16x32_bf16 v[36:39], v[44:47], v[146:149], v[138:141]
	s_mov_b32 m0, s42
	v_lshl_add_u64 v[246:247], s[18:19], 0, v[72:73]
	v_lshl_add_u64 v[246:247], v[246:247], 0, s[6:7]
	global_load_lds_dwordx4 v[246:247], off
	v_mfma_f32_16x16x32_bf16 v[40:43], v[44:47], v[56:59], v[142:145]
	s_mov_b32 m0, s43
	v_lshl_add_u64 v[246:247], s[18:19], 0, v[80:81]
	v_lshl_add_u64 v[246:247], v[246:247], 0, s[8:9]
	global_load_lds_dwordx4 v[246:247], off
	v_mfma_f32_16x16x32_bf16 v[44:47], v[44:47], v[60:63], v[110:113]
	v_mfma_f32_16x16x32_bf16 v[48:51], v[150:153], v[130:133], v[114:117]
	v_mfma_f32_16x16x32_bf16 v[52:55], v[150:153], v[146:149], v[122:125]
	v_mfma_f32_16x16x32_bf16 v[56:59], v[150:153], v[56:59], v[126:129]
	v_mfma_f32_16x16x32_bf16 v[60:63], v[150:153], v[60:63], v[118:121]
	s_setprio 0
	s_branch .LBB0_1336
